# RWKV scan: triangular solve and y mix as 2 f32 MFMAs with precomputed (I-Lab)^-1 and Mqb*T; rows permuted so solve outputs are B operands; v-part updates fill MFMA latency
# speedup vs baseline: 1.0248x; 1.0155x over previous
.LBB0_564:
	v_mov_b32_e32 v78, v75
	v_mov_b32_e32 v76, v77
	s_and_b32 s3, s40, 1
	v_add_u32_e32 v28, s72, v76
	v_ashrrev_i32_e32 v29, 31, v28
	v_lshlrev_b64 v[10:11], 2, v[28:29]
	v_lshl_add_u64 v[2:3], s[42:43], 0, v[10:11]
	global_load_dword v5, v[2:3], off
	global_load_dword v4, v[2:3], off offset:2048
	v_add_co_u32_e32 v2, vcc, s88, v2
	v_lshl_add_u64 v[6:7], s[44:45], 0, v[10:11]
	s_nop 0
	v_addc_co_u32_e32 v3, vcc, 0, v3, vcc
	v_lshl_add_u64 v[8:9], s[48:49], 0, v[10:11]
	global_load_dword v9, v[8:9], off
	s_nop 0
	global_load_dword v8, v[6:7], off
	s_nop 0
	global_load_dword v7, v[2:3], off
	v_lshl_add_u64 v[2:3], s[52:53], 0, v[10:11]
	global_load_dword v6, v[2:3], off
	v_lshl_add_u64 v[2:3], s[54:55], 0, v[10:11]
	global_load_dword v3, v[2:3], off
	v_lshl_add_u64 v[10:11], s[56:57], 0, v[10:11]
	global_load_dword v2, v[10:11], off
	s_mov_b64 s[0:1], src_shared_base
	s_cmp_lg_u32 0, -1
	v_sub_f32_e32 v14, v35, v46
	s_cselect_b32 s4, s1, 0
	s_cselect_b32 s5, 0, 0
	v_mad_u64_u32 v[10:11], s[0:1], v78, s87, v[76:77]
	s_add_u32 s0, s5, 0x11800
	v_lshl_add_u32 v16, v10, 2, 0
	s_addc_u32 s1, s4, 0
	s_cmp_lg_u64 s[0:1], 0
	s_cselect_b32 s6, s0, -1
	s_add_i32 s7, 0, 0x17800
	s_add_u32 s0, s5, 0x23800
	s_addc_u32 s1, s4, 0
	s_cmp_lg_u64 s[0:1], 0
	s_cselect_b32 s0, s0, -1
	s_add_i32 s1, 0, 0x1b800
	s_cmp_eq_u32 s3, 0
	s_cselect_b32 s16, s0, s1
	v_sub_f32_e32 v13, v106, v44
	s_cselect_b32 s41, s6, s7
	v_sub_f32_e32 v15, v34, v48
	v_lshl_add_u32 v12, v76, 2, s41
	v_lshlrev_b32_e32 v26, 3, v78
	v_cmp_eq_u32_e32 vcc, 0, v76
	s_waitcnt vmcnt(7)
	v_fma_f32 v13, v13, v5, v44
	s_waitcnt vmcnt(6)
	v_fma_f32 v14, v14, v4, v46
	s_waitcnt vmcnt(5)
	v_add_f32_e32 v10, v50, v9
	s_waitcnt vmcnt(4)
	v_add_f32_e32 v11, v107, v8
	v_mul_f32_e32 v10, 0xbfb8aa3b, v10
	v_mul_f32_e32 v11, 0xbfb8aa3b, v11
	s_waitcnt vmcnt(2)
	v_mul_f32_e32 v17, v14, v6
	v_exp_f32_e32 v10, v10
	v_exp_f32_e32 v11, v11
	v_mul_f32_e32 v18, v17, v17
	v_fma_f32 v15, v15, v7, v48
	v_add_f32_e32 v10, 1.0, v10
	v_mov_b32_dpp v18, v18 quad_perm:[1,0,3,2] row_mask:0xf bank_mask:0xf bound_ctrl:1
	v_fmac_f32_e32 v18, v17, v17
	v_add_f32_e32 v11, 1.0, v11
	v_rcp_f32_e32 v19, v10
	v_add_f32_dpp v18, v18, v18 quad_perm:[2,3,0,1] row_mask:0xf bank_mask:0xf bound_ctrl:1
	v_rcp_f32_e32 v20, v11
	s_nop 0
	v_add_f32_dpp v18, v18, v18 row_half_mirror row_mask:0xf bank_mask:0xf bound_ctrl:1
	s_nop 1
	v_add_f32_dpp v10, v18, v18 row_mirror row_mask:0xf bank_mask:0xf bound_ctrl:1
	v_mul_f32_e32 v18, 0xbf1b4598, v20
	v_readlane_b32 s3, v10, 16
	v_readlane_b32 s4, v10, 48
	v_readlane_b32 s0, v10, 0
	v_readlane_b32 s1, v10, 32
	v_mov_b32_e32 v10, s3
	v_mov_b32_e32 v11, s4
	v_pk_add_f32 v[10:11], s[0:1], v[10:11]
	v_mul_f32_e32 v18, 0x3fb8aa3b, v18
	v_add_f32_e32 v10, v10, v11
	v_add_f32_e32 v11, -1.0, v19
	v_add_f32_e32 v10, 0x2b8cbccc, v10
	s_waitcnt vmcnt(1)
	v_fma_f32 v20, v3, v11, 1.0
	v_exp_f32_e32 v11, v18
	v_mul_f32_e32 v18, 0x4b800000, v10
	v_cmp_gt_f32_e64 s[0:1], s91, v10
	v_mul_f32_e32 v14, v14, v20
	s_nop 0
	v_cndmask_b32_e64 v10, v10, v18, s[0:1]
	v_rsq_f32_e32 v10, v10
	v_mul_f32_e32 v18, v13, v14
	s_waitcnt vmcnt(0)
	v_mul_f32_e32 v20, v2, v18
	v_mul_f32_e32 v13, v13, v11
	v_mul_f32_e32 v21, 0x45800000, v10
	v_mov_b32_dpp v20, v20 quad_perm:[1,0,3,2] row_mask:0xf bank_mask:0xf bound_ctrl:1
	v_fmac_f32_e32 v20, v2, v18
	v_rcp_f32_e32 v18, v11
	v_cndmask_b32_e64 v10, v10, v21, s[0:1]
	v_mul_f32_e64 v10, v17, -v10
	v_add_f32_dpp v20, v20, v20 quad_perm:[2,3,0,1] row_mask:0xf bank_mask:0xf bound_ctrl:1
	ds_write2st64_b32 v16, v10, v13 offset1:68
	v_mul_f32_e64 v10, v19, -v10
	v_add_f32_dpp v20, v20, v20 row_half_mirror row_mask:0xf bank_mask:0xf bound_ctrl:1
	v_mul_f32_e32 v14, v18, v14
	v_mul_f32_e32 v10, v18, v10
	v_add_f32_dpp v20, v20, v20 row_mirror row_mask:0xf bank_mask:0xf bound_ctrl:1
	ds_write2st64_b32 v16, v10, v14 offset0:136 offset1:204
	v_lshl_add_u32 v10, v78, 11, v12
	v_readlane_b32 s0, v20, 0
	v_readlane_b32 s3, v20, 16
	v_readlane_b32 s1, v20, 32
	v_readlane_b32 s6, v20, 48
	ds_write_b32 v10, v15
	v_lshl_add_u32 v10, v26, 2, s16
	s_and_saveexec_b64 s[4:5], vcc
	v_mov_b32_e32 v14, s3
	v_mov_b32_e32 v15, s6
	v_pk_add_f32 v[14:15], s[0:1], v[14:15]
	s_nop 0
	v_add_f32_e32 v13, v14, v15
	ds_write_b32 v10, v13
	s_or_b64 exec, exec, s[4:5]
	v_add_f32_e32 v15, v51, v9
	v_mul_f32_e32 v15, 0xbfb8aa3b, v15
	v_add_f32_e32 v18, v108, v8
	v_exp_f32_e32 v15, v15
	v_mul_f32_e32 v18, 0xbfb8aa3b, v18
	v_exp_f32_e32 v18, v18
	v_sub_f32_e32 v13, v44, v1
	v_fma_f32 v17, v13, v5, v1
	v_sub_f32_e32 v13, v46, v45
	v_sub_f32_e32 v14, v48, v47
	v_fma_f32 v13, v13, v4, v45
	v_fma_f32 v19, v14, v7, v47
	v_add_f32_e32 v14, 1.0, v15
	v_rcp_f32_e32 v20, v14
	v_add_f32_e32 v14, 1.0, v18
	v_mul_f32_e32 v21, v13, v6
	v_rcp_f32_e32 v18, v14
	v_mul_f32_e32 v14, v21, v21
	v_or_b32_e32 v16, 1, v26
	s_nop 0
	v_mov_b32_dpp v14, v14 quad_perm:[1,0,3,2] row_mask:0xf bank_mask:0xf bound_ctrl:1
	v_fmac_f32_e32 v14, v21, v21
	s_nop 1
	v_add_f32_dpp v14, v14, v14 quad_perm:[2,3,0,1] row_mask:0xf bank_mask:0xf bound_ctrl:1
	s_nop 1
	v_add_f32_dpp v14, v14, v14 row_half_mirror row_mask:0xf bank_mask:0xf bound_ctrl:1
	s_nop 1
	v_add_f32_dpp v14, v14, v14 row_mirror row_mask:0xf bank_mask:0xf bound_ctrl:1
	s_nop 0
	v_readlane_b32 s3, v14, 16
	v_readlane_b32 s4, v14, 48
	v_readlane_b32 s0, v14, 0
	v_readlane_b32 s1, v14, 32
	v_mov_b32_e32 v14, s3
	v_mov_b32_e32 v15, s4
	v_pk_add_f32 v[14:15], s[0:1], v[14:15]
	s_movk_i32 s4, 0x44
	v_add_f32_e32 v14, v14, v15
	v_add_f32_e32 v14, 0x2b8cbccc, v14
	v_mul_f32_e32 v15, 0x4b800000, v14
	v_cmp_gt_f32_e64 s[0:1], s91, v14
	s_nop 1
	v_cndmask_b32_e64 v14, v14, v15, s[0:1]
	v_rsq_f32_e32 v14, v14
	v_mul_f32_e32 v15, 0xbf1b4598, v18
	v_mul_f32_e32 v15, 0x3fb8aa3b, v15
	v_exp_f32_e32 v15, v15
	v_mul_f32_e32 v18, 0x45800000, v14
	v_cndmask_b32_e64 v14, v14, v18, s[0:1]
	v_mul_f32_e32 v18, v21, v14
	v_add_f32_e32 v14, -1.0, v20
	v_fma_f32 v14, v3, v14, 1.0
	v_mul_f32_e32 v21, v13, v14
	v_mul_f32_e32 v13, v17, v21
	v_mul_f32_e32 v14, v2, v13
	v_mul_f32_e64 v23, v11, -v18
	s_nop 0
	v_mov_b32_dpp v14, v14 quad_perm:[1,0,3,2] row_mask:0xf bank_mask:0xf bound_ctrl:1
	v_fmac_f32_e32 v14, v2, v13
	s_nop 1
	v_add_f32_dpp v13, v14, v14 quad_perm:[2,3,0,1] row_mask:0xf bank_mask:0xf bound_ctrl:1
	s_nop 1
	v_add_f32_dpp v13, v13, v13 row_half_mirror row_mask:0xf bank_mask:0xf bound_ctrl:1
	s_nop 1
	v_add_f32_dpp v13, v13, v13 row_mirror row_mask:0xf bank_mask:0xf bound_ctrl:1
	s_nop 0
	v_readlane_b32 s0, v13, 0
	v_readlane_b32 s3, v13, 16
	v_readlane_b32 s1, v13, 32
	v_readlane_b32 s6, v13, 48
	v_mul_f32_e32 v13, v11, v15
	v_rcp_f32_e32 v22, v13
	v_mad_u64_u32 v[14:15], s[4:5], v16, s4, v[76:77]
	v_lshl_add_u32 v11, v14, 2, 0
	v_mul_f32_e32 v14, v17, v13
	ds_write2st64_b32 v11, v23, v14 offset1:68
	v_mul_f32_e32 v14, v20, v18
	v_mul_f32_e32 v14, v22, v14
	v_mul_f32_e32 v15, v22, v21
	ds_write2st64_b32 v11, v14, v15 offset0:136 offset1:204
	v_lshl_add_u32 v14, v16, 8, v12
	ds_write_b32 v14, v19
	s_and_saveexec_b64 s[4:5], vcc
	v_mov_b32_e32 v14, s3
	v_mov_b32_e32 v15, s6
	v_pk_add_f32 v[14:15], s[0:1], v[14:15]
	s_nop 0
	v_add_f32_e32 v14, v14, v15
	ds_write_b32 v10, v14 offset:4
	s_or_b64 exec, exec, s[4:5]
	v_add_f32_e32 v15, v58, v9
	v_mul_f32_e32 v15, 0xbfb8aa3b, v15
	v_add_f32_e32 v18, v109, v8
	v_exp_f32_e32 v15, v15
	v_mul_f32_e32 v18, 0xbfb8aa3b, v18
	v_sub_f32_e32 v14, v1, v52
	v_exp_f32_e32 v18, v18
	v_fma_f32 v16, v14, v5, v52
	v_sub_f32_e32 v14, v45, v54
	v_fma_f32 v17, v14, v4, v54
	v_sub_f32_e32 v14, v47, v56
	v_fma_f32 v19, v14, v7, v56
	v_add_f32_e32 v14, 1.0, v15
	v_rcp_f32_e32 v20, v14
	v_add_f32_e32 v14, 1.0, v18
	v_mul_f32_e32 v21, v17, v6
	v_rcp_f32_e32 v18, v14
	v_mul_f32_e32 v14, v21, v21
	v_lshl_add_u32 v12, v26, 8, v12
	s_nop 0
	v_mov_b32_dpp v14, v14 quad_perm:[1,0,3,2] row_mask:0xf bank_mask:0xf bound_ctrl:1
	v_fmac_f32_e32 v14, v21, v21
	s_nop 1
	v_add_f32_dpp v14, v14, v14 quad_perm:[2,3,0,1] row_mask:0xf bank_mask:0xf bound_ctrl:1
	s_nop 1
	v_add_f32_dpp v14, v14, v14 row_half_mirror row_mask:0xf bank_mask:0xf bound_ctrl:1
	s_nop 1
	v_add_f32_dpp v14, v14, v14 row_mirror row_mask:0xf bank_mask:0xf bound_ctrl:1
	s_nop 0
	v_readlane_b32 s3, v14, 16
	v_readlane_b32 s4, v14, 48
	v_readlane_b32 s0, v14, 0
	v_readlane_b32 s1, v14, 32
	v_mov_b32_e32 v14, s3
	v_mov_b32_e32 v15, s4
	v_pk_add_f32 v[14:15], s[0:1], v[14:15]
	s_nop 0
	v_add_f32_e32 v14, v14, v15
	v_add_f32_e32 v14, 0x2b8cbccc, v14
	v_mul_f32_e32 v15, 0x4b800000, v14
	v_cmp_gt_f32_e64 s[0:1], s91, v14
	s_nop 1
	v_cndmask_b32_e64 v14, v14, v15, s[0:1]
	v_rsq_f32_e32 v14, v14
	v_mul_f32_e32 v15, 0xbf1b4598, v18
	v_mul_f32_e32 v15, 0x3fb8aa3b, v15
	v_exp_f32_e32 v15, v15
	v_mul_f32_e32 v18, 0x45800000, v14
	v_cndmask_b32_e64 v14, v14, v18, s[0:1]
	v_mul_f32_e32 v18, v21, v14
	v_add_f32_e32 v14, -1.0, v20
	v_fma_f32 v14, v3, v14, 1.0
	v_mul_f32_e32 v17, v17, v14
	v_mul_f32_e32 v14, v16, v17
	v_mul_f32_e32 v21, v2, v14
	s_nop 1
	v_mov_b32_dpp v21, v21 quad_perm:[1,0,3,2] row_mask:0xf bank_mask:0xf bound_ctrl:1
	v_fmac_f32_e32 v21, v2, v14
	s_nop 1
	v_add_f32_dpp v14, v21, v21 quad_perm:[2,3,0,1] row_mask:0xf bank_mask:0xf bound_ctrl:1
	v_add_u32_e32 v21, 16, v11
	s_nop 0
	v_add_f32_dpp v14, v14, v14 row_half_mirror row_mask:0xf bank_mask:0xf bound_ctrl:1
	s_nop 1
	v_add_f32_dpp v14, v14, v14 row_mirror row_mask:0xf bank_mask:0xf bound_ctrl:1
	s_nop 0
	v_readlane_b32 s0, v14, 0
	v_readlane_b32 s3, v14, 16
	v_readlane_b32 s1, v14, 32
	v_readlane_b32 s6, v14, 48
	v_mul_f32_e32 v14, v15, v13
	v_rcp_f32_e32 v15, v14
	v_mul_f32_e64 v13, v13, -v18
	v_mul_f32_e32 v16, v16, v14
	ds_write2st64_b32 v21, v13, v16 offset0:1 offset1:69
	v_mul_f32_e32 v13, v20, v18
	v_mul_f32_e32 v13, v15, v13
	v_mul_f32_e32 v15, v17, v15
	ds_write2st64_b32 v21, v13, v15 offset0:137 offset1:205
	ds_write_b32 v12, v19 offset:512
	s_and_saveexec_b64 s[4:5], vcc
	v_mov_b32_e32 v16, s3
	v_mov_b32_e32 v17, s6
	v_pk_add_f32 v[16:17], s[0:1], v[16:17]
	s_nop 0
	v_add_f32_e32 v13, v16, v17
	ds_write_b32 v10, v13 offset:8
	s_or_b64 exec, exec, s[4:5]
	v_add_f32_e32 v17, v57, v9
	v_mul_f32_e32 v17, 0xbfb8aa3b, v17
	v_add_f32_e32 v18, v110, v8
	v_exp_f32_e32 v17, v17
	v_mul_f32_e32 v18, 0xbfb8aa3b, v18
	v_exp_f32_e32 v18, v18
	v_sub_f32_e32 v13, v52, v49
	v_fma_f32 v15, v13, v5, v49
	v_sub_f32_e32 v13, v54, v53
	v_sub_f32_e32 v16, v56, v55
	v_fma_f32 v13, v13, v4, v53
	v_fma_f32 v19, v16, v7, v55
	v_add_f32_e32 v16, 1.0, v17
	v_rcp_f32_e32 v20, v16
	v_add_f32_e32 v16, 1.0, v18
	v_mul_f32_e32 v21, v13, v6
	v_rcp_f32_e32 v18, v16
	v_mul_f32_e32 v16, v21, v21
	s_nop 1
	v_mov_b32_dpp v16, v16 quad_perm:[1,0,3,2] row_mask:0xf bank_mask:0xf bound_ctrl:1
	v_fmac_f32_e32 v16, v21, v21
	s_nop 1
	v_add_f32_dpp v16, v16, v16 quad_perm:[2,3,0,1] row_mask:0xf bank_mask:0xf bound_ctrl:1
	s_nop 1
	v_add_f32_dpp v16, v16, v16 row_half_mirror row_mask:0xf bank_mask:0xf bound_ctrl:1
	s_nop 1
	v_add_f32_dpp v16, v16, v16 row_mirror row_mask:0xf bank_mask:0xf bound_ctrl:1
	s_nop 0
	v_readlane_b32 s3, v16, 16
	v_readlane_b32 s4, v16, 48
	v_readlane_b32 s0, v16, 0
	v_readlane_b32 s1, v16, 32
	v_mov_b32_e32 v16, s3
	v_mov_b32_e32 v17, s4
	v_pk_add_f32 v[16:17], s[0:1], v[16:17]
	s_nop 0
	v_add_f32_e32 v16, v16, v17
	v_add_f32_e32 v16, 0x2b8cbccc, v16
	v_mul_f32_e32 v17, 0x4b800000, v16
	v_cmp_gt_f32_e64 s[0:1], s91, v16
	s_nop 1
	v_cndmask_b32_e64 v16, v16, v17, s[0:1]
	v_rsq_f32_e32 v16, v16
	v_mul_f32_e32 v17, 0xbf1b4598, v18
	v_mul_f32_e32 v17, 0x3fb8aa3b, v17
	v_exp_f32_e32 v17, v17
	v_mul_f32_e32 v18, 0x45800000, v16
	v_cndmask_b32_e64 v16, v16, v18, s[0:1]
	v_add_f32_e32 v18, -1.0, v20
	v_fma_f32 v18, v3, v18, 1.0
	v_mul_f32_e32 v18, v13, v18
	v_mul_f32_e32 v13, v15, v18
	v_mul_f32_e32 v16, v21, v16
	v_mul_f32_e32 v21, v2, v13
	s_nop 1
	v_mov_b32_dpp v21, v21 quad_perm:[1,0,3,2] row_mask:0xf bank_mask:0xf bound_ctrl:1
	v_fmac_f32_e32 v21, v2, v13
	s_nop 1
	v_add_f32_dpp v13, v21, v21 quad_perm:[2,3,0,1] row_mask:0xf bank_mask:0xf bound_ctrl:1
	v_add_u32_e32 v21, 32, v11
	s_nop 0
	v_add_f32_dpp v13, v13, v13 row_half_mirror row_mask:0xf bank_mask:0xf bound_ctrl:1
	s_nop 1
	v_add_f32_dpp v13, v13, v13 row_mirror row_mask:0xf bank_mask:0xf bound_ctrl:1
	s_nop 0
	v_readlane_b32 s0, v13, 0
	v_readlane_b32 s3, v13, 16
	v_readlane_b32 s1, v13, 32
	v_readlane_b32 s6, v13, 48
	v_mul_f32_e32 v13, v17, v14
	v_rcp_f32_e32 v17, v13
	v_mul_f32_e64 v14, v14, -v16
	v_mul_f32_e32 v15, v15, v13
	ds_write2st64_b32 v21, v14, v15 offset0:2 offset1:70
	v_mul_f32_e32 v14, v20, v16
	v_mul_f32_e32 v14, v17, v14
	v_mul_f32_e32 v15, v18, v17
	ds_write2st64_b32 v21, v14, v15 offset0:138 offset1:206
	ds_write_b32 v12, v19 offset:768
	s_and_saveexec_b64 s[4:5], vcc
	v_mov_b32_e32 v14, s3
	v_mov_b32_e32 v15, s6
	v_pk_add_f32 v[14:15], s[0:1], v[14:15]
	s_nop 0
	v_add_f32_e32 v14, v14, v15
	ds_write_b32 v10, v14 offset:12
	s_or_b64 exec, exec, s[4:5]
	v_add_f32_e32 v15, v66, v9
	v_mul_f32_e32 v15, 0xbfb8aa3b, v15
	v_add_f32_e32 v18, v111, v8
	v_exp_f32_e32 v15, v15
	v_mul_f32_e32 v18, 0xbfb8aa3b, v18
	v_sub_f32_e32 v14, v49, v60
	v_exp_f32_e32 v18, v18
	v_fma_f32 v16, v14, v5, v60
	v_sub_f32_e32 v14, v53, v62
	v_fma_f32 v17, v14, v4, v62
	v_sub_f32_e32 v14, v55, v64
	v_fma_f32 v19, v14, v7, v64
	v_add_f32_e32 v14, 1.0, v15
	v_rcp_f32_e32 v20, v14
	v_add_f32_e32 v14, 1.0, v18
	v_mul_f32_e32 v21, v17, v6
	v_rcp_f32_e32 v18, v14
	v_mul_f32_e32 v14, v21, v21
	s_nop 1
	v_mov_b32_dpp v14, v14 quad_perm:[1,0,3,2] row_mask:0xf bank_mask:0xf bound_ctrl:1
	v_fmac_f32_e32 v14, v21, v21
	s_nop 1
	v_add_f32_dpp v14, v14, v14 quad_perm:[2,3,0,1] row_mask:0xf bank_mask:0xf bound_ctrl:1
	s_nop 1
	v_add_f32_dpp v14, v14, v14 row_half_mirror row_mask:0xf bank_mask:0xf bound_ctrl:1
	s_nop 1
	v_add_f32_dpp v14, v14, v14 row_mirror row_mask:0xf bank_mask:0xf bound_ctrl:1
	s_nop 0
	v_readlane_b32 s3, v14, 16
	v_readlane_b32 s4, v14, 48
	v_readlane_b32 s0, v14, 0
	v_readlane_b32 s1, v14, 32
	v_mov_b32_e32 v14, s3
	v_mov_b32_e32 v15, s4
	v_pk_add_f32 v[14:15], s[0:1], v[14:15]
	s_nop 0
	v_add_f32_e32 v14, v14, v15
	v_add_f32_e32 v14, 0x2b8cbccc, v14
	v_mul_f32_e32 v15, 0x4b800000, v14
	v_cmp_gt_f32_e64 s[0:1], s91, v14
	s_nop 1
	v_cndmask_b32_e64 v14, v14, v15, s[0:1]
	v_rsq_f32_e32 v14, v14
	v_mul_f32_e32 v15, 0xbf1b4598, v18
	v_mul_f32_e32 v15, 0x3fb8aa3b, v15
	v_exp_f32_e32 v15, v15
	v_mul_f32_e32 v18, 0x45800000, v14
	v_cndmask_b32_e64 v14, v14, v18, s[0:1]
	v_mul_f32_e32 v18, v21, v14
	v_add_f32_e32 v14, -1.0, v20
	v_fma_f32 v14, v3, v14, 1.0
	v_mul_f32_e32 v17, v17, v14
	v_mul_f32_e32 v14, v16, v17
	v_mul_f32_e32 v21, v2, v14
	s_nop 1
	v_mov_b32_dpp v21, v21 quad_perm:[1,0,3,2] row_mask:0xf bank_mask:0xf bound_ctrl:1
	v_fmac_f32_e32 v21, v2, v14
	s_nop 1
	v_add_f32_dpp v14, v21, v21 quad_perm:[2,3,0,1] row_mask:0xf bank_mask:0xf bound_ctrl:1
	v_add_u32_e32 v21, 48, v11
	s_nop 0
	v_add_f32_dpp v14, v14, v14 row_half_mirror row_mask:0xf bank_mask:0xf bound_ctrl:1
	s_nop 1
	v_add_f32_dpp v14, v14, v14 row_mirror row_mask:0xf bank_mask:0xf bound_ctrl:1
	s_nop 0
	v_readlane_b32 s0, v14, 0
	v_readlane_b32 s3, v14, 16
	v_readlane_b32 s1, v14, 32
	v_readlane_b32 s6, v14, 48
	v_mul_f32_e32 v14, v15, v13
	v_rcp_f32_e32 v15, v14
	v_mul_f32_e64 v13, v13, -v18
	v_mul_f32_e32 v16, v16, v14
	ds_write2st64_b32 v21, v13, v16 offset0:3 offset1:71
	v_mul_f32_e32 v13, v20, v18
	v_mul_f32_e32 v13, v15, v13
	v_mul_f32_e32 v15, v17, v15
	ds_write2st64_b32 v21, v13, v15 offset0:139 offset1:207
	ds_write_b32 v12, v19 offset:1024
	s_and_saveexec_b64 s[4:5], vcc
	v_mov_b32_e32 v16, s3
	v_mov_b32_e32 v17, s6
	v_pk_add_f32 v[16:17], s[0:1], v[16:17]
	s_nop 0
	v_add_f32_e32 v13, v16, v17
	ds_write_b32 v10, v13 offset:16
	s_or_b64 exec, exec, s[4:5]
	v_add_f32_e32 v17, v65, v9
	v_mul_f32_e32 v17, 0xbfb8aa3b, v17
	v_add_f32_e32 v18, v112, v8
	v_exp_f32_e32 v17, v17
	v_mul_f32_e32 v18, 0xbfb8aa3b, v18
	v_exp_f32_e32 v18, v18
	v_sub_f32_e32 v13, v60, v59
	v_fma_f32 v15, v13, v5, v59
	v_sub_f32_e32 v13, v62, v61
	v_sub_f32_e32 v16, v64, v63
	v_fma_f32 v13, v13, v4, v61
	v_fma_f32 v19, v16, v7, v63
	v_add_f32_e32 v16, 1.0, v17
	v_rcp_f32_e32 v20, v16
	v_add_f32_e32 v16, 1.0, v18
	v_mul_f32_e32 v21, v13, v6
	v_rcp_f32_e32 v18, v16
	v_mul_f32_e32 v16, v21, v21
	s_nop 1
	v_mov_b32_dpp v16, v16 quad_perm:[1,0,3,2] row_mask:0xf bank_mask:0xf bound_ctrl:1
	v_fmac_f32_e32 v16, v21, v21
	s_nop 1
	v_add_f32_dpp v16, v16, v16 quad_perm:[2,3,0,1] row_mask:0xf bank_mask:0xf bound_ctrl:1
	s_nop 1
	v_add_f32_dpp v16, v16, v16 row_half_mirror row_mask:0xf bank_mask:0xf bound_ctrl:1
	s_nop 1
	v_add_f32_dpp v16, v16, v16 row_mirror row_mask:0xf bank_mask:0xf bound_ctrl:1
	s_nop 0
	v_readlane_b32 s3, v16, 16
	v_readlane_b32 s4, v16, 48
	v_readlane_b32 s0, v16, 0
	v_readlane_b32 s1, v16, 32
	v_mov_b32_e32 v16, s3
	v_mov_b32_e32 v17, s4
	v_pk_add_f32 v[16:17], s[0:1], v[16:17]
	s_nop 0
	v_add_f32_e32 v16, v16, v17
	v_add_f32_e32 v16, 0x2b8cbccc, v16
	v_mul_f32_e32 v17, 0x4b800000, v16
	v_cmp_gt_f32_e64 s[0:1], s91, v16
	s_nop 1
	v_cndmask_b32_e64 v16, v16, v17, s[0:1]
	v_rsq_f32_e32 v16, v16
	v_mul_f32_e32 v17, 0xbf1b4598, v18
	v_mul_f32_e32 v17, 0x3fb8aa3b, v17
	v_exp_f32_e32 v17, v17
	v_mul_f32_e32 v18, 0x45800000, v16
	v_cndmask_b32_e64 v16, v16, v18, s[0:1]
	v_add_f32_e32 v18, -1.0, v20
	v_fma_f32 v18, v3, v18, 1.0
	v_mul_f32_e32 v18, v13, v18
	v_mul_f32_e32 v13, v15, v18
	v_mul_f32_e32 v16, v21, v16
	v_mul_f32_e32 v21, v2, v13
	s_nop 1
	v_mov_b32_dpp v21, v21 quad_perm:[1,0,3,2] row_mask:0xf bank_mask:0xf bound_ctrl:1
	v_fmac_f32_e32 v21, v2, v13
	s_nop 1
	v_add_f32_dpp v13, v21, v21 quad_perm:[2,3,0,1] row_mask:0xf bank_mask:0xf bound_ctrl:1
	v_add_u32_e32 v21, 64, v11
	s_nop 0
	v_add_f32_dpp v13, v13, v13 row_half_mirror row_mask:0xf bank_mask:0xf bound_ctrl:1
	s_nop 1
	v_add_f32_dpp v13, v13, v13 row_mirror row_mask:0xf bank_mask:0xf bound_ctrl:1
	s_nop 0
	v_readlane_b32 s0, v13, 0
	v_readlane_b32 s3, v13, 16
	v_readlane_b32 s1, v13, 32
	v_readlane_b32 s6, v13, 48
	v_mul_f32_e32 v13, v17, v14
	v_rcp_f32_e32 v17, v13
	v_mul_f32_e64 v14, v14, -v16
	v_mul_f32_e32 v15, v15, v13
	ds_write2st64_b32 v21, v14, v15 offset0:4 offset1:72
	v_mul_f32_e32 v14, v20, v16
	v_mul_f32_e32 v14, v17, v14
	v_mul_f32_e32 v15, v18, v17
	ds_write2st64_b32 v21, v14, v15 offset0:140 offset1:208
	ds_write_b32 v12, v19 offset:1280
	s_and_saveexec_b64 s[4:5], vcc
	v_mov_b32_e32 v14, s3
	v_mov_b32_e32 v15, s6
	v_pk_add_f32 v[14:15], s[0:1], v[14:15]
	s_nop 0
	v_add_f32_e32 v14, v14, v15
	ds_write_b32 v10, v14 offset:20
	s_or_b64 exec, exec, s[4:5]
	v_add_f32_e32 v15, v74, v9
	v_mul_f32_e32 v15, 0xbfb8aa3b, v15
	v_add_f32_e32 v18, v113, v8
	v_exp_f32_e32 v15, v15
	v_mul_f32_e32 v18, 0xbfb8aa3b, v18
	v_sub_f32_e32 v14, v59, v67
	v_exp_f32_e32 v18, v18
	v_fma_f32 v16, v14, v5, v67
	v_sub_f32_e32 v14, v61, v69
	v_fma_f32 v17, v14, v4, v69
	v_sub_f32_e32 v14, v63, v71
	v_fma_f32 v19, v14, v7, v71
	v_add_f32_e32 v14, 1.0, v15
	v_rcp_f32_e32 v20, v14
	v_add_f32_e32 v14, 1.0, v18
	v_mul_f32_e32 v21, v17, v6
	v_rcp_f32_e32 v18, v14
	v_mul_f32_e32 v14, v21, v21
	s_nop 1
	v_mov_b32_dpp v14, v14 quad_perm:[1,0,3,2] row_mask:0xf bank_mask:0xf bound_ctrl:1
	v_fmac_f32_e32 v14, v21, v21
	s_nop 1
	v_add_f32_dpp v14, v14, v14 quad_perm:[2,3,0,1] row_mask:0xf bank_mask:0xf bound_ctrl:1
	s_nop 1
	v_add_f32_dpp v14, v14, v14 row_half_mirror row_mask:0xf bank_mask:0xf bound_ctrl:1
	s_nop 1
	v_add_f32_dpp v14, v14, v14 row_mirror row_mask:0xf bank_mask:0xf bound_ctrl:1
	s_nop 0
	v_readlane_b32 s3, v14, 16
	v_readlane_b32 s4, v14, 48
	v_readlane_b32 s0, v14, 0
	v_readlane_b32 s1, v14, 32
	v_mov_b32_e32 v14, s3
	v_mov_b32_e32 v15, s4
	v_pk_add_f32 v[14:15], s[0:1], v[14:15]
	s_nop 0
	v_add_f32_e32 v14, v14, v15
	v_add_f32_e32 v14, 0x2b8cbccc, v14
	v_mul_f32_e32 v15, 0x4b800000, v14
	v_cmp_gt_f32_e64 s[0:1], s91, v14
	s_nop 1
	v_cndmask_b32_e64 v14, v14, v15, s[0:1]
	v_rsq_f32_e32 v14, v14
	v_mul_f32_e32 v15, 0xbf1b4598, v18
	v_mul_f32_e32 v15, 0x3fb8aa3b, v15
	v_exp_f32_e32 v15, v15
	v_mul_f32_e32 v18, 0x45800000, v14
	v_cndmask_b32_e64 v14, v14, v18, s[0:1]
	v_mul_f32_e32 v18, v21, v14
	v_add_f32_e32 v14, -1.0, v20
	v_fma_f32 v14, v3, v14, 1.0
	v_mul_f32_e32 v17, v17, v14
	v_mul_f32_e32 v14, v16, v17
	v_mul_f32_e32 v21, v2, v14
	s_nop 1
	v_mov_b32_dpp v21, v21 quad_perm:[1,0,3,2] row_mask:0xf bank_mask:0xf bound_ctrl:1
	v_fmac_f32_e32 v21, v2, v14
	s_nop 1
	v_add_f32_dpp v14, v21, v21 quad_perm:[2,3,0,1] row_mask:0xf bank_mask:0xf bound_ctrl:1
	v_add_u32_e32 v21, 0x50, v11
	s_nop 0
	v_add_f32_dpp v14, v14, v14 row_half_mirror row_mask:0xf bank_mask:0xf bound_ctrl:1
	s_nop 1
	v_add_f32_dpp v14, v14, v14 row_mirror row_mask:0xf bank_mask:0xf bound_ctrl:1
	s_nop 0
	v_readlane_b32 s0, v14, 0
	v_readlane_b32 s3, v14, 16
	v_readlane_b32 s1, v14, 32
	v_readlane_b32 s6, v14, 48
	v_mul_f32_e32 v14, v15, v13
	v_rcp_f32_e32 v15, v14
	v_mul_f32_e64 v13, v13, -v18
	v_mul_f32_e32 v16, v16, v14
	ds_write2st64_b32 v21, v13, v16 offset0:5 offset1:73
	v_mul_f32_e32 v13, v20, v18
	v_mul_f32_e32 v13, v15, v13
	v_mul_f32_e32 v15, v17, v15
	ds_write2st64_b32 v21, v13, v15 offset0:141 offset1:209
	ds_write_b32 v12, v19 offset:1536
	s_and_saveexec_b64 s[4:5], vcc
	v_mov_b32_e32 v16, s3
	v_mov_b32_e32 v17, s6
	v_pk_add_f32 v[16:17], s[0:1], v[16:17]
	s_nop 0
	v_add_f32_e32 v13, v16, v17
	ds_write_b32 v10, v13 offset:24
	s_or_b64 exec, exec, s[4:5]
	v_sub_f32_e32 v13, v67, v68
	v_fma_f32 v13, v13, v5, v68
	v_sub_f32_e32 v5, v69, v70
	v_fma_f32 v15, v5, v4, v70
	v_add_f32_e32 v5, v73, v9
	v_mul_f32_e32 v5, 0xbfb8aa3b, v5
	v_add_f32_e32 v8, v114, v8
	v_exp_f32_e32 v5, v5
	v_mul_f32_e32 v8, 0xbfb8aa3b, v8
	v_exp_f32_e32 v8, v8
	v_sub_f32_e32 v4, v71, v72
	v_fma_f32 v7, v4, v7, v72
	v_add_f32_e32 v4, 1.0, v5
	v_rcp_f32_e32 v9, v4
	v_add_f32_e32 v4, 1.0, v8
	v_mul_f32_e32 v6, v15, v6
	v_rcp_f32_e32 v8, v4
	v_mul_f32_e32 v4, v6, v6
	v_add_u32_e32 v11, 0x60, v11
	s_nop 0
	v_mov_b32_dpp v4, v4 quad_perm:[1,0,3,2] row_mask:0xf bank_mask:0xf bound_ctrl:1
	v_fmac_f32_e32 v4, v6, v6
	s_nop 1
	v_add_f32_dpp v4, v4, v4 quad_perm:[2,3,0,1] row_mask:0xf bank_mask:0xf bound_ctrl:1
	s_nop 1
	v_add_f32_dpp v4, v4, v4 row_half_mirror row_mask:0xf bank_mask:0xf bound_ctrl:1
	s_nop 1
	v_add_f32_dpp v4, v4, v4 row_mirror row_mask:0xf bank_mask:0xf bound_ctrl:1
	s_nop 0
	v_readlane_b32 s3, v4, 16
	v_readlane_b32 s4, v4, 48
	v_readlane_b32 s0, v4, 0
	v_readlane_b32 s1, v4, 32
	v_mov_b32_e32 v4, s3
	v_mov_b32_e32 v5, s4
	v_pk_add_f32 v[4:5], s[0:1], v[4:5]
	s_nop 0
	v_add_f32_e32 v4, v4, v5
	v_add_f32_e32 v4, 0x2b8cbccc, v4
	v_mul_f32_e32 v5, 0x4b800000, v4
	v_cmp_gt_f32_e64 s[0:1], s91, v4
	s_nop 1
	v_cndmask_b32_e64 v4, v4, v5, s[0:1]
	v_rsq_f32_e32 v4, v4
	v_mul_f32_e32 v5, 0xbf1b4598, v8
	v_mul_f32_e32 v5, 0x3fb8aa3b, v5
	v_exp_f32_e32 v5, v5
	v_mul_f32_e32 v8, 0x45800000, v4
	v_cndmask_b32_e64 v4, v4, v8, s[0:1]
	v_mul_f32_e32 v4, v6, v4
	v_add_f32_e32 v6, -1.0, v9
	v_fma_f32 v3, v3, v6, 1.0
	v_mul_f32_e32 v3, v15, v3
	v_mul_f32_e32 v6, v13, v3
	v_mul_f32_e32 v8, v2, v6
	s_nop 1
	v_mov_b32_dpp v8, v8 quad_perm:[1,0,3,2] row_mask:0xf bank_mask:0xf bound_ctrl:1
	v_fmac_f32_e32 v8, v2, v6
	v_mul_f32_e64 v6, v14, -v4
	v_mul_f32_e32 v4, v9, v4
	v_add_f32_dpp v2, v8, v8 quad_perm:[2,3,0,1] row_mask:0xf bank_mask:0xf bound_ctrl:1
	s_nop 1
	v_add_f32_dpp v2, v2, v2 row_half_mirror row_mask:0xf bank_mask:0xf bound_ctrl:1
	s_nop 1
	v_add_f32_dpp v2, v2, v2 row_mirror row_mask:0xf bank_mask:0xf bound_ctrl:1
	s_nop 0
	v_readlane_b32 s0, v2, 0
	v_readlane_b32 s3, v2, 16
	v_readlane_b32 s1, v2, 32
	v_readlane_b32 s6, v2, 48
	v_mul_f32_e32 v2, v5, v14
	v_rcp_f32_e32 v5, v2
	v_mul_f32_e32 v8, v13, v2
	ds_write2st64_b32 v11, v6, v8 offset0:6 offset1:74
	v_mul_f32_e32 v4, v5, v4
	v_mul_f32_e32 v3, v3, v5
	ds_write2st64_b32 v11, v4, v3 offset0:142 offset1:210
	ds_write_b32 v12, v7 offset:1792
	s_and_saveexec_b64 s[4:5], vcc
	v_mov_b32_e32 v4, s3
	v_mov_b32_e32 v5, s6
	v_pk_add_f32 v[4:5], s[0:1], v[4:5]
	s_nop 0
	v_add_f32_e32 v3, v4, v5
	ds_write_b32 v10, v3 offset:28
	s_or_b64 exec, exec, s[4:5]
	v_lshlrev_b32_e32 v3, 8, v78
	v_lshlrev_b32_e32 v4, 2, v76
	v_add3_u32 v3, s92, v3, v4
	ds_write_b32 v3, v2
	v_and_b32_e32 v124, 15, v76
	v_lshrrev_b32_e32 v125, 4, v76
	v_and_b32_e32 v132, 7, v124
	v_add_u32_e32 v126, v26, v132
	v_mul_u32_u24_e32 v126, 0x110, v126
	v_lshl_add_u32 v126, v125, 4, v126
	v_and_b32_e32 v127, 8, v124
	v_mul_u32_u24_e32 v127, 0x880, v127
	v_add_u32_e32 v128, v126, v127
	v_add_u32_e32 v129, 0x8800, v128
	ds_read_b128 v[136:139], v128 offset:0
	ds_read_b128 v[152:155], v129 offset:0
	ds_read_b128 v[140:143], v128 offset:64
	ds_read_b128 v[156:159], v129 offset:64
	ds_read_b128 v[144:147], v128 offset:128
	ds_read_b128 v[160:163], v129 offset:128
	ds_read_b128 v[148:151], v128 offset:192
	ds_read_b128 v[164:167], v129 offset:192
	v_lshrrev_b32_e32 v126, 1, v125
	v_lshrrev_b32_e32 v127, 3, v124
	v_lshl_add_u32 v127, v126, 1, v127
	v_lshlrev_b32_e32 v130, 8, v127
	v_lshl_add_u32 v130, v26, 7, v130
	v_and_b32_e32 v127, 1, v125
	v_lshl_add_u32 v130, v127, 7, v130
	v_lshl_add_u32 v130, v132, 2, v130
	v_add_u32_e32 v130, 0x15800, v130
	v_sub_u32_e32 v131, 1, v126
	v_add_u32_e32 v131, v131, v132
	v_lshlrev_b32_e32 v127, 2, v127
	v_sub_u32_e32 v131, v131, v127
	v_max_i32_e32 v131, 0, v131
	v_cmp_ge_u32_e64 s[0:1], 1, v131
	v_cmp_ge_u32_e64 s[4:5], 2, v131
	v_cmp_ge_u32_e64 s[6:7], 3, v131
	v_cmp_ge_u32_e32 vcc, 0, v131
	s_waitcnt lgkmcnt(0)
	v_mfma_f32_16x16x4_f32 v[36:39], v136, v152, 0
	v_mfma_f32_16x16x4_f32 v[40:43], v137, v153, 0
	v_mfma_f32_16x16x4_f32 v[36:39], v138, v154, v[36:39]
	v_mfma_f32_16x16x4_f32 v[40:43], v139, v155, v[40:43]
	v_mfma_f32_16x16x4_f32 v[36:39], v140, v156, v[36:39]
	v_mfma_f32_16x16x4_f32 v[40:43], v141, v157, v[40:43]
	v_mfma_f32_16x16x4_f32 v[36:39], v142, v158, v[36:39]
	v_mfma_f32_16x16x4_f32 v[40:43], v143, v159, v[40:43]
	v_mfma_f32_16x16x4_f32 v[36:39], v144, v160, v[36:39]
	v_mfma_f32_16x16x4_f32 v[40:43], v145, v161, v[40:43]
	v_mfma_f32_16x16x4_f32 v[36:39], v146, v162, v[36:39]
	v_mfma_f32_16x16x4_f32 v[40:43], v147, v163, v[40:43]
	v_mfma_f32_16x16x4_f32 v[36:39], v148, v164, v[36:39]
	v_mfma_f32_16x16x4_f32 v[40:43], v149, v165, v[40:43]
	v_mfma_f32_16x16x4_f32 v[36:39], v150, v166, v[36:39]
	v_mfma_f32_16x16x4_f32 v[40:43], v151, v167, v[40:43]
	s_nop 7
	s_nop 2
	v_pk_add_f32 v[36:37], v[36:37], v[40:41]
	v_pk_add_f32 v[38:39], v[38:39], v[42:43]
	v_cndmask_b32_e32 v36, 0, v36, vcc
	v_cndmask_b32_e64 v37, 0, v37, s[0:1]
	v_cndmask_b32_e64 v38, 0, v38, s[4:5]
	v_cndmask_b32_e64 v39, 0, v39, s[6:7]
	ds_write_b32 v130, v36 offset:0
	ds_write_b32 v130, v37 offset:32
	ds_write_b32 v130, v38 offset:64
	ds_write_b32 v130, v39 offset:96
	v_mov_b32_e32 v168, v132
	v_lshlrev_b32_e32 v169, 7, v26
	v_add_u32_e32 v169, 0x15800, v169
	v_lshl_add_u32 v172, v125, 6, v169
	v_lshl_add_u32 v170, v132, 2, v169
	v_lshl_add_u32 v173, v132, 2, v172
	v_mov_b32_e32 v171, 1.0
	ds_read_b128 v[124:127], v169 offset:32
	ds_read_b128 v[128:131], v169 offset:64
	ds_read_b128 v[132:135], v169 offset:96
	ds_read_b128 v[136:139], v169 offset:128
	ds_read_b128 v[144:147], v169 offset:160
	ds_read_b128 v[148:151], v169 offset:176
	ds_read_b128 v[152:155], v169 offset:192
	ds_read_b128 v[156:159], v169 offset:208
	ds_read_b128 v[160:163], v169 offset:224
	ds_read_b128 v[164:167], v169 offset:240
	ds_read_b128 v[182:185], v172 offset:512
	ds_read_b128 v[186:189], v172 offset:528
	ds_read_b128 v[190:193], v172 offset:544
	ds_read_b128 v[194:197], v172 offset:560
	v_cmp_eq_u32_e32 vcc, 0, v168
	v_cndmask_b32_e32 v36, 0, v171, vcc
	v_cmp_eq_u32_e32 vcc, 1, v168
	v_cndmask_b32_e32 v37, 0, v171, vcc
	v_cmp_eq_u32_e32 vcc, 2, v168
	v_cndmask_b32_e32 v38, 0, v171, vcc
	v_cmp_eq_u32_e32 vcc, 3, v168
	v_cndmask_b32_e32 v39, 0, v171, vcc
	v_cmp_eq_u32_e32 vcc, 4, v168
	v_cndmask_b32_e32 v40, 0, v171, vcc
	v_cmp_eq_u32_e32 vcc, 5, v168
	v_cndmask_b32_e32 v41, 0, v171, vcc
	v_cmp_eq_u32_e32 vcc, 6, v168
	v_cndmask_b32_e32 v42, 0, v171, vcc
	v_cmp_eq_u32_e32 vcc, 7, v168
	v_cndmask_b32_e32 v43, 0, v171, vcc
	s_waitcnt lgkmcnt(0)
	v_fmac_f32_e32 v37, v124, v36
	v_fmac_f32_e32 v38, v128, v36
	v_fmac_f32_e32 v39, v132, v36
	v_fmac_f32_e32 v40, v136, v36
	v_fmac_f32_e32 v41, v144, v36
	v_fmac_f32_e32 v42, v152, v36
	v_fmac_f32_e32 v43, v160, v36
	v_fmac_f32_e32 v38, v129, v37
	v_fmac_f32_e32 v39, v133, v37
	v_fmac_f32_e32 v40, v137, v37
	v_fmac_f32_e32 v41, v145, v37
	v_fmac_f32_e32 v42, v153, v37
	v_fmac_f32_e32 v43, v161, v37
	v_fmac_f32_e32 v39, v134, v38
	v_fmac_f32_e32 v40, v138, v38
	v_fmac_f32_e32 v41, v146, v38
	v_fmac_f32_e32 v42, v154, v38
	v_fmac_f32_e32 v43, v162, v38
	v_fmac_f32_e32 v40, v139, v39
	v_fmac_f32_e32 v41, v147, v39
	v_fmac_f32_e32 v42, v155, v39
	v_fmac_f32_e32 v43, v163, v39
	v_fmac_f32_e32 v41, v148, v40
	v_fmac_f32_e32 v42, v156, v40
	v_fmac_f32_e32 v43, v164, v40
	v_fmac_f32_e32 v42, v157, v41
	v_fmac_f32_e32 v43, v165, v41
	v_fmac_f32_e32 v43, v166, v42
	v_mul_f32_e32 v44, v182, v36
	v_fmac_f32_e32 v44, v183, v37
	v_fmac_f32_e32 v44, v184, v38
	v_fmac_f32_e32 v44, v185, v39
	v_fmac_f32_e32 v44, v186, v40
	v_fmac_f32_e32 v44, v187, v41
	v_fmac_f32_e32 v44, v188, v42
	v_fmac_f32_e32 v44, v189, v43
	v_mul_f32_e32 v45, v190, v36
	v_fmac_f32_e32 v45, v191, v37
	v_fmac_f32_e32 v45, v192, v38
	v_fmac_f32_e32 v45, v193, v39
	v_fmac_f32_e32 v45, v194, v40
	v_fmac_f32_e32 v45, v195, v41
	v_fmac_f32_e32 v45, v196, v42
	v_fmac_f32_e32 v45, v197, v43
	ds_write_b32 v170, v36 offset:0
	ds_write_b32 v170, v37 offset:32
	ds_write_b32 v170, v38 offset:64
	ds_write_b32 v170, v39 offset:96
	ds_write_b32 v170, v40 offset:128
	ds_write_b32 v170, v41 offset:160
	ds_write_b32 v170, v42 offset:192
	ds_write_b32 v170, v43 offset:224
	ds_write_b32 v173, v44 offset:512
	ds_write_b32 v173, v45 offset:544
	s_lshl_b32 s17, s40, 6
	s_cmp_lg_u32 s40, 31
	s_waitcnt lgkmcnt(0)
	s_barrier
	s_cbranch_scc0 .LBB0_586
	s_add_i32 s3, s17, 64
	s_add_u32 s0, s80, s3
	s_addc_u32 s1, s81, 0
	v_ashrrev_i32_e32 v27, 31, v26
	v_lshl_add_u64 v[4:5], s[0:1], 0, v[26:27]
	v_mad_u64_u32 v[2:3], s[0:1], v4, s83, 0
	v_mad_i32_i24 v3, v5, s83, v3
	v_add_u32_e32 v1, s3, v26
	v_mov_b32_e32 v95, v94
	v_lshl_add_u64 v[2:3], s[46:47], 0, v[2:3]
	v_cmp_lt_i32_e32 vcc, 0, v1
	v_mov_b32_e32 v106, 0
	v_lshl_add_u64 v[2:3], v[28:29], 1, v[2:3]
	v_mov_b64_e32 v[34:35], v[94:95]
	s_and_saveexec_b64 s[0:1], vcc
	s_cbranch_execz .LBB0_585
	global_load_ushort v52, v[2:3], off offset:-3072
	global_load_ushort v53, v[2:3], off offset:-2048
	global_load_ushort v54, v[2:3], off offset:-1024

.LBB0_586:
.Lrw_entry:
	v_readfirstlane_b32 s0, v180
	s_nop 1
	s_cmpk_ge_u32 s0, 0x100
	s_cbranch_scc1 .Lrw_epi
	v_and_b32_e32 v222, 15, v180
	v_bfe_u32 v223, v180, 4, 2
	v_lshrrev_b32_e32 v240, 6, v180
	v_lshrrev_b32_e32 v176, 2, v222
	v_and_b32_e32 v177, 1, v222
	v_lshl_add_u32 v176, v177, 2, v176
	v_lshlrev_b32_e32 v171, 5, v176
	v_mul_u32_u24_e32 v176, 0x110, v176
	v_and_b32_e32 v177, 2, v222
	v_lshl_add_u32 v171, v177, 8, v171
	v_lshl_add_u32 v171, v223, 2, v171
	v_add_u32_e32 v171, 0x15800, v171
	v_mul_u32_u24_e32 v177, 0x2200, v177
	v_lshl_add_u32 v168, v223, 4, v176
	v_add_u32_e32 v168, v168, v177
	v_lshlrev_b32_e32 v178, 6, v240
	v_lshl_add_u32 v178, v222, 2, v178
	v_lshl_add_u32 v178, v223, 8, v178
	v_add_u32_e32 v169, s41, v178
	v_add_u32_e32 v175, 0x1f800, v178
	v_mul_u32_u24_e32 v176, 0x110, v223
	v_lshl_add_u32 v173, v222, 2, v176
	v_add_u32_e32 v173, 0x8800, v173
	v_add_u32_e32 v2, 0x440, v173
	v_add_u32_e32 v3, 0x4400, v173
	v_add_u32_e32 v5, 0x4840, v173
	v_lshlrev_b32_e32 v174, 4, v223
	v_add_u32_e32 v174, 0x11000, v174
	s_mov_b32 s14, 0
	s_mov_b32 s15, 1
	v_mov_b32_e32 v179, 0x27f00
	v_mov_b32_e32 v241, 1
	v_mov_b32_e32 v80, 0
	v_mov_b32_e32 v81, 0
	v_mov_b32_e32 v198, 1.0
	v_mov_b32_e32 v199, 1.0
	v_mov_b32_e32 v200, 1.0
	v_mov_b32_e32 v201, 1.0
	v_mov_b32_e32 v202, 1.0
	v_mov_b32_e32 v203, 1.0
	v_mov_b32_e32 v204, 1.0
	v_mov_b32_e32 v205, 1.0
	v_mov_b32_e32 v206, 1.0
	v_mov_b32_e32 v207, 1.0
	v_mov_b32_e32 v208, 1.0
	v_mov_b32_e32 v209, 1.0
	v_mov_b32_e32 v210, 1.0
	v_mov_b32_e32 v211, 1.0
	v_mov_b32_e32 v212, 1.0
	v_mov_b32_e32 v213, 1.0
	ds_read_b128 v[44:47], v168 offset:0
	ds_read_b128 v[48:51], v168 offset:64
	ds_read_b128 v[68:71], v168 offset:128
	ds_read_b128 v[96:99], v168 offset:192
	ds_read_b32 v216, v171 offset:256
	ds_read_b32 v217, v171 offset:272
	ds_read_b32 v214, v169 offset:0
	ds_read_b32 v215, v169 offset:1024
	ds_read_b32 v218, v171 offset:0
	ds_read_b32 v219, v171 offset:16
	ds_read2_b32 v[182:183], v173 offset0:0 offset1:16
	ds_read2_b32 v[184:185], v173 offset0:32 offset1:48
	ds_read2_b32 v[186:187], v2 offset0:0 offset1:16
	ds_read2_b32 v[188:189], v2 offset0:32 offset1:48
	ds_read2_b32 v[190:191], v3 offset0:0 offset1:16
	ds_read2_b32 v[192:193], v3 offset0:32 offset1:48
	ds_read2_b32 v[194:195], v5 offset0:0 offset1:16
	ds_read2_b32 v[196:197], v5 offset0:32 offset1:48
	s_mov_b32 s1, 0
	s_waitcnt lgkmcnt(0)
	v_pk_mul_f32 v[224:225], v[224:225], v[198:199]
	v_pk_mul_f32 v[226:227], v[226:227], v[200:201]
	v_pk_mul_f32 v[228:229], v[228:229], v[202:203]
	v_pk_mul_f32 v[230:231], v[230:231], v[204:205]
	v_mfma_f32_16x16x4_f32 v[36:39], v44, v224, 0
	v_mfma_f32_16x16x4_f32 v[40:43], v45, v225, 0
	v_mfma_f32_16x16x4_f32 v[36:39], v46, v226, v[36:39]
	v_mfma_f32_16x16x4_f32 v[40:43], v47, v227, v[40:43]
	v_pk_mul_f32 v[232:233], v[232:233], v[206:207]
	v_pk_mul_f32 v[234:235], v[234:235], v[208:209]
	v_mfma_f32_16x16x4_f32 v[36:39], v48, v228, v[36:39]
	v_mfma_f32_16x16x4_f32 v[40:43], v49, v229, v[40:43]
	v_mfma_f32_16x16x4_f32 v[36:39], v50, v230, v[36:39]
	v_mfma_f32_16x16x4_f32 v[40:43], v51, v231, v[40:43]
	v_pk_mul_f32 v[236:237], v[236:237], v[210:211]
	v_pk_mul_f32 v[238:239], v[238:239], v[212:213]
	v_mfma_f32_16x16x4_f32 v[36:39], v68, v232, v[36:39]
	v_mfma_f32_16x16x4_f32 v[40:43], v69, v233, v[40:43]
	v_mfma_f32_16x16x4_f32 v[36:39], v70, v234, v[36:39]
	v_mfma_f32_16x16x4_f32 v[40:43], v71, v235, v[40:43]
	v_mfma_f32_16x16x4_f32 v[36:39], v96, v236, v[36:39]
	v_mfma_f32_16x16x4_f32 v[40:43], v97, v237, v[40:43]
	v_mfma_f32_16x16x4_f32 v[36:39], v98, v238, v[36:39]
	v_mfma_f32_16x16x4_f32 v[40:43], v99, v239, v[40:43]
	v_mfma_f32_16x16x4_f32 v[36:39], v216, v214, v[36:39]
	v_mfma_f32_16x16x4_f32 v[40:43], v217, v215, v[40:43]
	v_mfma_f32_16x16x4_f32 v[224:227], v190, v214, v[224:227]
	v_mfma_f32_16x16x4_f32 v[228:231], v191, v214, v[228:231]
	v_mfma_f32_16x16x4_f32 v[232:235], v192, v214, v[232:235]
	v_mfma_f32_16x16x4_f32 v[236:239], v193, v214, v[236:239]
	ds_read_b128 v[44:47], v168 offset:2176
	ds_read_b128 v[48:51], v168 offset:2240
	ds_read_b128 v[68:71], v168 offset:2304
	ds_read_b128 v[96:99], v168 offset:2368
	ds_read_b32 v216, v171 offset:1280
	ds_read_b32 v217, v171 offset:1296
	v_pk_add_f32 v[84:85], v[36:37], v[40:41]
	v_pk_add_f32 v[82:83], v[38:39], v[42:43]
	s_nop 1
	v_mfma_f32_16x16x4_f32 v[88:91], v218, v84, v[80:83]
	v_mfma_f32_16x16x4_f32 v[88:91], v219, v85, v[88:91]
	v_mfma_f32_16x16x4_f32 v[224:227], v194, v215, v[224:227]
	v_mfma_f32_16x16x4_f32 v[228:231], v195, v215, v[228:231]
	v_mfma_f32_16x16x4_f32 v[232:235], v196, v215, v[232:235]
	v_mfma_f32_16x16x4_f32 v[236:239], v197, v215, v[236:239]
	ds_read_b128 v[198:201], v174 offset:0
	ds_read_b128 v[202:205], v174 offset:64
	ds_read_b128 v[206:209], v174 offset:128
	ds_read_b128 v[210:213], v174 offset:192
	ds_read_b32 v218, v171 offset:1024
	ds_read_b32 v219, v171 offset:1040
	ds_read_b32 v214, v169 offset:2048
	ds_read_b32 v215, v169 offset:3072
	v_mfma_f32_16x16x4_f32 v[224:227], v182, v88, v[224:227]
	v_mfma_f32_16x16x4_f32 v[228:231], v183, v88, v[228:231]
	v_mfma_f32_16x16x4_f32 v[232:235], v184, v88, v[232:235]
	v_mfma_f32_16x16x4_f32 v[236:239], v185, v88, v[236:239]
	v_mfma_f32_16x16x4_f32 v[224:227], v186, v89, v[224:227]
	v_mfma_f32_16x16x4_f32 v[228:231], v187, v89, v[228:231]
	v_mfma_f32_16x16x4_f32 v[232:235], v188, v89, v[232:235]
	v_mfma_f32_16x16x4_f32 v[236:239], v189, v89, v[236:239]
	v_add_u32_e32 v173, 0x880, v173
	v_add_u32_e32 v2, 0x880, v2
	v_add_u32_e32 v3, 0x880, v3
	v_add_u32_e32 v5, 0x880, v5
	ds_read2_b32 v[182:183], v173 offset0:0 offset1:16
	ds_read2_b32 v[184:185], v173 offset0:32 offset1:48
	ds_read2_b32 v[186:187], v2 offset0:0 offset1:16
	ds_read2_b32 v[188:189], v2 offset0:32 offset1:48
	ds_read2_b32 v[190:191], v3 offset0:0 offset1:16
	ds_read2_b32 v[192:193], v3 offset0:32 offset1:48
	ds_read2_b32 v[194:195], v5 offset0:0 offset1:16
	ds_read2_b32 v[196:197], v5 offset0:32 offset1:48
	ds_write2st64_b32 v175, v90, v91 offset0:0 offset1:4
	s_mov_b64 exec, s[14:15]
	ds_add_u32 v179, v241 offset:0
	s_mov_b64 exec, -1
	s_waitcnt lgkmcnt(14)
	v_pk_mul_f32 v[224:225], v[224:225], v[198:199]
	v_pk_mul_f32 v[226:227], v[226:227], v[200:201]
	v_pk_mul_f32 v[228:229], v[228:229], v[202:203]
	v_pk_mul_f32 v[230:231], v[230:231], v[204:205]
	v_mfma_f32_16x16x4_f32 v[36:39], v44, v224, 0
	v_mfma_f32_16x16x4_f32 v[40:43], v45, v225, 0
	v_mfma_f32_16x16x4_f32 v[36:39], v46, v226, v[36:39]
	v_mfma_f32_16x16x4_f32 v[40:43], v47, v227, v[40:43]
	v_pk_mul_f32 v[232:233], v[232:233], v[206:207]
	v_pk_mul_f32 v[234:235], v[234:235], v[208:209]
	v_mfma_f32_16x16x4_f32 v[36:39], v48, v228, v[36:39]
	v_mfma_f32_16x16x4_f32 v[40:43], v49, v229, v[40:43]
	v_mfma_f32_16x16x4_f32 v[36:39], v50, v230, v[36:39]
	v_mfma_f32_16x16x4_f32 v[40:43], v51, v231, v[40:43]
	v_pk_mul_f32 v[236:237], v[236:237], v[210:211]
	v_pk_mul_f32 v[238:239], v[238:239], v[212:213]
	v_mfma_f32_16x16x4_f32 v[36:39], v68, v232, v[36:39]
	v_mfma_f32_16x16x4_f32 v[40:43], v69, v233, v[40:43]
	v_mfma_f32_16x16x4_f32 v[36:39], v70, v234, v[36:39]
	v_mfma_f32_16x16x4_f32 v[40:43], v71, v235, v[40:43]
	v_mfma_f32_16x16x4_f32 v[36:39], v96, v236, v[36:39]
	v_mfma_f32_16x16x4_f32 v[40:43], v97, v237, v[40:43]
	v_mfma_f32_16x16x4_f32 v[36:39], v98, v238, v[36:39]
	v_mfma_f32_16x16x4_f32 v[40:43], v99, v239, v[40:43]
	s_waitcnt lgkmcnt(2)
	v_mfma_f32_16x16x4_f32 v[36:39], v216, v214, v[36:39]
	v_mfma_f32_16x16x4_f32 v[40:43], v217, v215, v[40:43]
	v_mfma_f32_16x16x4_f32 v[224:227], v190, v214, v[224:227]
	v_mfma_f32_16x16x4_f32 v[228:231], v191, v214, v[228:231]
	v_mfma_f32_16x16x4_f32 v[232:235], v192, v214, v[232:235]
	v_mfma_f32_16x16x4_f32 v[236:239], v193, v214, v[236:239]
	ds_read_b128 v[44:47], v168 offset:4352
	ds_read_b128 v[48:51], v168 offset:4416
	ds_read_b128 v[68:71], v168 offset:4480
	ds_read_b128 v[96:99], v168 offset:4544
	ds_read_b32 v216, v171 offset:2304
	ds_read_b32 v217, v171 offset:2320
	v_pk_add_f32 v[84:85], v[36:37], v[40:41]
	v_pk_add_f32 v[82:83], v[38:39], v[42:43]
	s_nop 1
	v_mfma_f32_16x16x4_f32 v[88:91], v218, v84, v[80:83]
	v_mfma_f32_16x16x4_f32 v[88:91], v219, v85, v[88:91]
	v_mfma_f32_16x16x4_f32 v[224:227], v194, v215, v[224:227]
	v_mfma_f32_16x16x4_f32 v[228:231], v195, v215, v[228:231]
	v_mfma_f32_16x16x4_f32 v[232:235], v196, v215, v[232:235]
	v_mfma_f32_16x16x4_f32 v[236:239], v197, v215, v[236:239]
	ds_read_b128 v[198:201], v174 offset:256
	ds_read_b128 v[202:205], v174 offset:320
	ds_read_b128 v[206:209], v174 offset:384
	ds_read_b128 v[210:213], v174 offset:448
	ds_read_b32 v218, v171 offset:2048
	ds_read_b32 v219, v171 offset:2064
	ds_read_b32 v214, v169 offset:4096
	ds_read_b32 v215, v169 offset:5120
	v_mfma_f32_16x16x4_f32 v[224:227], v182, v88, v[224:227]
	v_mfma_f32_16x16x4_f32 v[228:231], v183, v88, v[228:231]
	v_mfma_f32_16x16x4_f32 v[232:235], v184, v88, v[232:235]
	v_mfma_f32_16x16x4_f32 v[236:239], v185, v88, v[236:239]
	v_mfma_f32_16x16x4_f32 v[224:227], v186, v89, v[224:227]
	v_mfma_f32_16x16x4_f32 v[228:231], v187, v89, v[228:231]
	v_mfma_f32_16x16x4_f32 v[232:235], v188, v89, v[232:235]
	v_mfma_f32_16x16x4_f32 v[236:239], v189, v89, v[236:239]
	v_add_u32_e32 v173, 0x880, v173
	v_add_u32_e32 v2, 0x880, v2
	v_add_u32_e32 v3, 0x880, v3
	v_add_u32_e32 v5, 0x880, v5
	ds_read2_b32 v[182:183], v173 offset0:0 offset1:16
	ds_read2_b32 v[184:185], v173 offset0:32 offset1:48
	ds_read2_b32 v[186:187], v2 offset0:0 offset1:16
	ds_read2_b32 v[188:189], v2 offset0:32 offset1:48
	ds_read2_b32 v[190:191], v3 offset0:0 offset1:16
	ds_read2_b32 v[192:193], v3 offset0:32 offset1:48
	ds_read2_b32 v[194:195], v5 offset0:0 offset1:16
	ds_read2_b32 v[196:197], v5 offset0:32 offset1:48
	ds_write2st64_b32 v175, v90, v91 offset0:8 offset1:12
	s_mov_b64 exec, s[14:15]
	ds_add_u32 v179, v241 offset:4
	s_mov_b64 exec, -1
	s_waitcnt lgkmcnt(14)
	v_pk_mul_f32 v[224:225], v[224:225], v[198:199]
	v_pk_mul_f32 v[226:227], v[226:227], v[200:201]
	v_pk_mul_f32 v[228:229], v[228:229], v[202:203]
	v_pk_mul_f32 v[230:231], v[230:231], v[204:205]
	v_mfma_f32_16x16x4_f32 v[36:39], v44, v224, 0
	v_mfma_f32_16x16x4_f32 v[40:43], v45, v225, 0
	v_mfma_f32_16x16x4_f32 v[36:39], v46, v226, v[36:39]
	v_mfma_f32_16x16x4_f32 v[40:43], v47, v227, v[40:43]
	v_pk_mul_f32 v[232:233], v[232:233], v[206:207]
	v_pk_mul_f32 v[234:235], v[234:235], v[208:209]
	v_mfma_f32_16x16x4_f32 v[36:39], v48, v228, v[36:39]
	v_mfma_f32_16x16x4_f32 v[40:43], v49, v229, v[40:43]
	v_mfma_f32_16x16x4_f32 v[36:39], v50, v230, v[36:39]
	v_mfma_f32_16x16x4_f32 v[40:43], v51, v231, v[40:43]
	v_pk_mul_f32 v[236:237], v[236:237], v[210:211]
	v_pk_mul_f32 v[238:239], v[238:239], v[212:213]
	v_mfma_f32_16x16x4_f32 v[36:39], v68, v232, v[36:39]
	v_mfma_f32_16x16x4_f32 v[40:43], v69, v233, v[40:43]
	v_mfma_f32_16x16x4_f32 v[36:39], v70, v234, v[36:39]
	v_mfma_f32_16x16x4_f32 v[40:43], v71, v235, v[40:43]
	v_mfma_f32_16x16x4_f32 v[36:39], v96, v236, v[36:39]
	v_mfma_f32_16x16x4_f32 v[40:43], v97, v237, v[40:43]
	v_mfma_f32_16x16x4_f32 v[36:39], v98, v238, v[36:39]
	v_mfma_f32_16x16x4_f32 v[40:43], v99, v239, v[40:43]
	s_waitcnt lgkmcnt(2)
	v_mfma_f32_16x16x4_f32 v[36:39], v216, v214, v[36:39]
	v_mfma_f32_16x16x4_f32 v[40:43], v217, v215, v[40:43]
	v_mfma_f32_16x16x4_f32 v[224:227], v190, v214, v[224:227]
	v_mfma_f32_16x16x4_f32 v[228:231], v191, v214, v[228:231]
	v_mfma_f32_16x16x4_f32 v[232:235], v192, v214, v[232:235]
	v_mfma_f32_16x16x4_f32 v[236:239], v193, v214, v[236:239]
	ds_read_b128 v[44:47], v168 offset:6528
	ds_read_b128 v[48:51], v168 offset:6592
	ds_read_b128 v[68:71], v168 offset:6656
	ds_read_b128 v[96:99], v168 offset:6720
	ds_read_b32 v216, v171 offset:3328
	ds_read_b32 v217, v171 offset:3344
	v_pk_add_f32 v[84:85], v[36:37], v[40:41]
	v_pk_add_f32 v[82:83], v[38:39], v[42:43]
	s_nop 1
	v_mfma_f32_16x16x4_f32 v[88:91], v218, v84, v[80:83]
	v_mfma_f32_16x16x4_f32 v[88:91], v219, v85, v[88:91]
	v_mfma_f32_16x16x4_f32 v[224:227], v194, v215, v[224:227]
	v_mfma_f32_16x16x4_f32 v[228:231], v195, v215, v[228:231]
	v_mfma_f32_16x16x4_f32 v[232:235], v196, v215, v[232:235]
	v_mfma_f32_16x16x4_f32 v[236:239], v197, v215, v[236:239]
	ds_read_b128 v[198:201], v174 offset:512
	ds_read_b128 v[202:205], v174 offset:576
	ds_read_b128 v[206:209], v174 offset:640
	ds_read_b128 v[210:213], v174 offset:704
	ds_read_b32 v218, v171 offset:3072
	ds_read_b32 v219, v171 offset:3088
	ds_read_b32 v214, v169 offset:6144
	ds_read_b32 v215, v169 offset:7168
	v_mfma_f32_16x16x4_f32 v[224:227], v182, v88, v[224:227]
	v_mfma_f32_16x16x4_f32 v[228:231], v183, v88, v[228:231]
	v_mfma_f32_16x16x4_f32 v[232:235], v184, v88, v[232:235]
	v_mfma_f32_16x16x4_f32 v[236:239], v185, v88, v[236:239]
	v_mfma_f32_16x16x4_f32 v[224:227], v186, v89, v[224:227]
	v_mfma_f32_16x16x4_f32 v[228:231], v187, v89, v[228:231]
	v_mfma_f32_16x16x4_f32 v[232:235], v188, v89, v[232:235]
	v_mfma_f32_16x16x4_f32 v[236:239], v189, v89, v[236:239]
	v_add_u32_e32 v173, 0x880, v173
	v_add_u32_e32 v2, 0x880, v2
	v_add_u32_e32 v3, 0x880, v3
	v_add_u32_e32 v5, 0x880, v5
	ds_read2_b32 v[182:183], v173 offset0:0 offset1:16
	ds_read2_b32 v[184:185], v173 offset0:32 offset1:48
	ds_read2_b32 v[186:187], v2 offset0:0 offset1:16
	ds_read2_b32 v[188:189], v2 offset0:32 offset1:48
	ds_read2_b32 v[190:191], v3 offset0:0 offset1:16
	ds_read2_b32 v[192:193], v3 offset0:32 offset1:48
	ds_read2_b32 v[194:195], v5 offset0:0 offset1:16
	ds_read2_b32 v[196:197], v5 offset0:32 offset1:48
	ds_write2st64_b32 v175, v90, v91 offset0:16 offset1:20
	s_mov_b64 exec, s[14:15]
	ds_add_u32 v179, v241 offset:8
	s_mov_b64 exec, -1
	s_waitcnt lgkmcnt(14)
	v_pk_mul_f32 v[224:225], v[224:225], v[198:199]
	v_pk_mul_f32 v[226:227], v[226:227], v[200:201]
	v_pk_mul_f32 v[228:229], v[228:229], v[202:203]
	v_pk_mul_f32 v[230:231], v[230:231], v[204:205]
	v_mfma_f32_16x16x4_f32 v[36:39], v44, v224, 0
	v_mfma_f32_16x16x4_f32 v[40:43], v45, v225, 0
	v_mfma_f32_16x16x4_f32 v[36:39], v46, v226, v[36:39]
	v_mfma_f32_16x16x4_f32 v[40:43], v47, v227, v[40:43]
	v_pk_mul_f32 v[232:233], v[232:233], v[206:207]
	v_pk_mul_f32 v[234:235], v[234:235], v[208:209]
	v_mfma_f32_16x16x4_f32 v[36:39], v48, v228, v[36:39]
	v_mfma_f32_16x16x4_f32 v[40:43], v49, v229, v[40:43]
	v_mfma_f32_16x16x4_f32 v[36:39], v50, v230, v[36:39]
	v_mfma_f32_16x16x4_f32 v[40:43], v51, v231, v[40:43]
	v_pk_mul_f32 v[236:237], v[236:237], v[210:211]
	v_pk_mul_f32 v[238:239], v[238:239], v[212:213]
	v_mfma_f32_16x16x4_f32 v[36:39], v68, v232, v[36:39]
	v_mfma_f32_16x16x4_f32 v[40:43], v69, v233, v[40:43]
	v_mfma_f32_16x16x4_f32 v[36:39], v70, v234, v[36:39]
	v_mfma_f32_16x16x4_f32 v[40:43], v71, v235, v[40:43]
	v_mfma_f32_16x16x4_f32 v[36:39], v96, v236, v[36:39]
	v_mfma_f32_16x16x4_f32 v[40:43], v97, v237, v[40:43]
	v_mfma_f32_16x16x4_f32 v[36:39], v98, v238, v[36:39]
	v_mfma_f32_16x16x4_f32 v[40:43], v99, v239, v[40:43]
	s_waitcnt lgkmcnt(2)
	v_mfma_f32_16x16x4_f32 v[36:39], v216, v214, v[36:39]
	v_mfma_f32_16x16x4_f32 v[40:43], v217, v215, v[40:43]
	v_mfma_f32_16x16x4_f32 v[224:227], v190, v214, v[224:227]
	v_mfma_f32_16x16x4_f32 v[228:231], v191, v214, v[228:231]
	v_mfma_f32_16x16x4_f32 v[232:235], v192, v214, v[232:235]
	v_mfma_f32_16x16x4_f32 v[236:239], v193, v214, v[236:239]
	ds_read_b128 v[44:47], v168 offset:8704
	ds_read_b128 v[48:51], v168 offset:8768
	ds_read_b128 v[68:71], v168 offset:8832
	ds_read_b128 v[96:99], v168 offset:8896
	ds_read_b32 v216, v171 offset:4352
	ds_read_b32 v217, v171 offset:4368
	v_pk_add_f32 v[84:85], v[36:37], v[40:41]
	v_pk_add_f32 v[82:83], v[38:39], v[42:43]
	s_nop 1
	v_mfma_f32_16x16x4_f32 v[88:91], v218, v84, v[80:83]
	v_mfma_f32_16x16x4_f32 v[88:91], v219, v85, v[88:91]
	v_mfma_f32_16x16x4_f32 v[224:227], v194, v215, v[224:227]
	v_mfma_f32_16x16x4_f32 v[228:231], v195, v215, v[228:231]
	v_mfma_f32_16x16x4_f32 v[232:235], v196, v215, v[232:235]
	v_mfma_f32_16x16x4_f32 v[236:239], v197, v215, v[236:239]
	ds_read_b128 v[198:201], v174 offset:768
	ds_read_b128 v[202:205], v174 offset:832
	ds_read_b128 v[206:209], v174 offset:896
	ds_read_b128 v[210:213], v174 offset:960
	ds_read_b32 v218, v171 offset:4096
	ds_read_b32 v219, v171 offset:4112
	ds_read_b32 v214, v169 offset:8192
	ds_read_b32 v215, v169 offset:9216
	v_mfma_f32_16x16x4_f32 v[224:227], v182, v88, v[224:227]
	v_mfma_f32_16x16x4_f32 v[228:231], v183, v88, v[228:231]
	v_mfma_f32_16x16x4_f32 v[232:235], v184, v88, v[232:235]
	v_mfma_f32_16x16x4_f32 v[236:239], v185, v88, v[236:239]
	v_mfma_f32_16x16x4_f32 v[224:227], v186, v89, v[224:227]
	v_mfma_f32_16x16x4_f32 v[228:231], v187, v89, v[228:231]
	v_mfma_f32_16x16x4_f32 v[232:235], v188, v89, v[232:235]
	v_mfma_f32_16x16x4_f32 v[236:239], v189, v89, v[236:239]
	v_add_u32_e32 v173, 0x880, v173
	v_add_u32_e32 v2, 0x880, v2
	v_add_u32_e32 v3, 0x880, v3
	v_add_u32_e32 v5, 0x880, v5
	ds_read2_b32 v[182:183], v173 offset0:0 offset1:16
	ds_read2_b32 v[184:185], v173 offset0:32 offset1:48
	ds_read2_b32 v[186:187], v2 offset0:0 offset1:16
	ds_read2_b32 v[188:189], v2 offset0:32 offset1:48
	ds_read2_b32 v[190:191], v3 offset0:0 offset1:16
	ds_read2_b32 v[192:193], v3 offset0:32 offset1:48
	ds_read2_b32 v[194:195], v5 offset0:0 offset1:16
	ds_read2_b32 v[196:197], v5 offset0:32 offset1:48
	ds_write2st64_b32 v175, v90, v91 offset0:24 offset1:28
	s_mov_b64 exec, s[14:15]
	ds_add_u32 v179, v241 offset:12
	s_mov_b64 exec, -1
	s_waitcnt lgkmcnt(14)
	v_pk_mul_f32 v[224:225], v[224:225], v[198:199]
	v_pk_mul_f32 v[226:227], v[226:227], v[200:201]
	v_pk_mul_f32 v[228:229], v[228:229], v[202:203]
	v_pk_mul_f32 v[230:231], v[230:231], v[204:205]
	v_mfma_f32_16x16x4_f32 v[36:39], v44, v224, 0
	v_mfma_f32_16x16x4_f32 v[40:43], v45, v225, 0
	v_mfma_f32_16x16x4_f32 v[36:39], v46, v226, v[36:39]
	v_mfma_f32_16x16x4_f32 v[40:43], v47, v227, v[40:43]
	v_pk_mul_f32 v[232:233], v[232:233], v[206:207]
	v_pk_mul_f32 v[234:235], v[234:235], v[208:209]
	v_mfma_f32_16x16x4_f32 v[36:39], v48, v228, v[36:39]
	v_mfma_f32_16x16x4_f32 v[40:43], v49, v229, v[40:43]
	v_mfma_f32_16x16x4_f32 v[36:39], v50, v230, v[36:39]
	v_mfma_f32_16x16x4_f32 v[40:43], v51, v231, v[40:43]
	v_pk_mul_f32 v[236:237], v[236:237], v[210:211]
	v_pk_mul_f32 v[238:239], v[238:239], v[212:213]
	v_mfma_f32_16x16x4_f32 v[36:39], v68, v232, v[36:39]
	v_mfma_f32_16x16x4_f32 v[40:43], v69, v233, v[40:43]
	v_mfma_f32_16x16x4_f32 v[36:39], v70, v234, v[36:39]
	v_mfma_f32_16x16x4_f32 v[40:43], v71, v235, v[40:43]
	v_mfma_f32_16x16x4_f32 v[36:39], v96, v236, v[36:39]
	v_mfma_f32_16x16x4_f32 v[40:43], v97, v237, v[40:43]
	v_mfma_f32_16x16x4_f32 v[36:39], v98, v238, v[36:39]
	v_mfma_f32_16x16x4_f32 v[40:43], v99, v239, v[40:43]
	s_waitcnt lgkmcnt(2)
	v_mfma_f32_16x16x4_f32 v[36:39], v216, v214, v[36:39]
	v_mfma_f32_16x16x4_f32 v[40:43], v217, v215, v[40:43]
	v_mfma_f32_16x16x4_f32 v[224:227], v190, v214, v[224:227]
	v_mfma_f32_16x16x4_f32 v[228:231], v191, v214, v[228:231]
	v_mfma_f32_16x16x4_f32 v[232:235], v192, v214, v[232:235]
	v_mfma_f32_16x16x4_f32 v[236:239], v193, v214, v[236:239]
	ds_read_b128 v[44:47], v168 offset:10880
	ds_read_b128 v[48:51], v168 offset:10944
	ds_read_b128 v[68:71], v168 offset:11008
	ds_read_b128 v[96:99], v168 offset:11072
	ds_read_b32 v216, v171 offset:5376
	ds_read_b32 v217, v171 offset:5392
	v_pk_add_f32 v[84:85], v[36:37], v[40:41]
	v_pk_add_f32 v[82:83], v[38:39], v[42:43]
	s_nop 1
	v_mfma_f32_16x16x4_f32 v[88:91], v218, v84, v[80:83]
	v_mfma_f32_16x16x4_f32 v[88:91], v219, v85, v[88:91]
	v_mfma_f32_16x16x4_f32 v[224:227], v194, v215, v[224:227]
	v_mfma_f32_16x16x4_f32 v[228:231], v195, v215, v[228:231]
	v_mfma_f32_16x16x4_f32 v[232:235], v196, v215, v[232:235]
	v_mfma_f32_16x16x4_f32 v[236:239], v197, v215, v[236:239]
	ds_read_b128 v[198:201], v174 offset:1024
	ds_read_b128 v[202:205], v174 offset:1088
	ds_read_b128 v[206:209], v174 offset:1152
	ds_read_b128 v[210:213], v174 offset:1216
	ds_read_b32 v218, v171 offset:5120
	ds_read_b32 v219, v171 offset:5136
	ds_read_b32 v214, v169 offset:10240
	ds_read_b32 v215, v169 offset:11264
	v_mfma_f32_16x16x4_f32 v[224:227], v182, v88, v[224:227]
	v_mfma_f32_16x16x4_f32 v[228:231], v183, v88, v[228:231]
	v_mfma_f32_16x16x4_f32 v[232:235], v184, v88, v[232:235]
	v_mfma_f32_16x16x4_f32 v[236:239], v185, v88, v[236:239]
	v_mfma_f32_16x16x4_f32 v[224:227], v186, v89, v[224:227]
	v_mfma_f32_16x16x4_f32 v[228:231], v187, v89, v[228:231]
	v_mfma_f32_16x16x4_f32 v[232:235], v188, v89, v[232:235]
	v_mfma_f32_16x16x4_f32 v[236:239], v189, v89, v[236:239]
	v_add_u32_e32 v173, 0x880, v173
	v_add_u32_e32 v2, 0x880, v2
	v_add_u32_e32 v3, 0x880, v3
	v_add_u32_e32 v5, 0x880, v5
	ds_read2_b32 v[182:183], v173 offset0:0 offset1:16
	ds_read2_b32 v[184:185], v173 offset0:32 offset1:48
	ds_read2_b32 v[186:187], v2 offset0:0 offset1:16
	ds_read2_b32 v[188:189], v2 offset0:32 offset1:48
	ds_read2_b32 v[190:191], v3 offset0:0 offset1:16
	ds_read2_b32 v[192:193], v3 offset0:32 offset1:48
	ds_read2_b32 v[194:195], v5 offset0:0 offset1:16
	ds_read2_b32 v[196:197], v5 offset0:32 offset1:48
	ds_write2st64_b32 v175, v90, v91 offset0:32 offset1:36
	s_mov_b64 exec, s[14:15]
	ds_add_u32 v179, v241 offset:16
	s_mov_b64 exec, -1
	s_waitcnt lgkmcnt(14)
	v_pk_mul_f32 v[224:225], v[224:225], v[198:199]
	v_pk_mul_f32 v[226:227], v[226:227], v[200:201]
	v_pk_mul_f32 v[228:229], v[228:229], v[202:203]
	v_pk_mul_f32 v[230:231], v[230:231], v[204:205]
	v_mfma_f32_16x16x4_f32 v[36:39], v44, v224, 0
	v_mfma_f32_16x16x4_f32 v[40:43], v45, v225, 0
	v_mfma_f32_16x16x4_f32 v[36:39], v46, v226, v[36:39]
	v_mfma_f32_16x16x4_f32 v[40:43], v47, v227, v[40:43]
	v_pk_mul_f32 v[232:233], v[232:233], v[206:207]
	v_pk_mul_f32 v[234:235], v[234:235], v[208:209]
	v_mfma_f32_16x16x4_f32 v[36:39], v48, v228, v[36:39]
	v_mfma_f32_16x16x4_f32 v[40:43], v49, v229, v[40:43]
	v_mfma_f32_16x16x4_f32 v[36:39], v50, v230, v[36:39]
	v_mfma_f32_16x16x4_f32 v[40:43], v51, v231, v[40:43]
	v_pk_mul_f32 v[236:237], v[236:237], v[210:211]
	v_pk_mul_f32 v[238:239], v[238:239], v[212:213]
	v_mfma_f32_16x16x4_f32 v[36:39], v68, v232, v[36:39]
	v_mfma_f32_16x16x4_f32 v[40:43], v69, v233, v[40:43]
	v_mfma_f32_16x16x4_f32 v[36:39], v70, v234, v[36:39]
	v_mfma_f32_16x16x4_f32 v[40:43], v71, v235, v[40:43]
	v_mfma_f32_16x16x4_f32 v[36:39], v96, v236, v[36:39]
	v_mfma_f32_16x16x4_f32 v[40:43], v97, v237, v[40:43]
	v_mfma_f32_16x16x4_f32 v[36:39], v98, v238, v[36:39]
	v_mfma_f32_16x16x4_f32 v[40:43], v99, v239, v[40:43]
	s_waitcnt lgkmcnt(2)
	v_mfma_f32_16x16x4_f32 v[36:39], v216, v214, v[36:39]
	v_mfma_f32_16x16x4_f32 v[40:43], v217, v215, v[40:43]
	v_mfma_f32_16x16x4_f32 v[224:227], v190, v214, v[224:227]
	v_mfma_f32_16x16x4_f32 v[228:231], v191, v214, v[228:231]
	v_mfma_f32_16x16x4_f32 v[232:235], v192, v214, v[232:235]
	v_mfma_f32_16x16x4_f32 v[236:239], v193, v214, v[236:239]
	ds_read_b128 v[44:47], v168 offset:13056
	ds_read_b128 v[48:51], v168 offset:13120
	ds_read_b128 v[68:71], v168 offset:13184
	ds_read_b128 v[96:99], v168 offset:13248
	ds_read_b32 v216, v171 offset:6400
	ds_read_b32 v217, v171 offset:6416
	v_pk_add_f32 v[84:85], v[36:37], v[40:41]
	v_pk_add_f32 v[82:83], v[38:39], v[42:43]
	s_nop 1
	v_mfma_f32_16x16x4_f32 v[88:91], v218, v84, v[80:83]
	v_mfma_f32_16x16x4_f32 v[88:91], v219, v85, v[88:91]
	v_mfma_f32_16x16x4_f32 v[224:227], v194, v215, v[224:227]
	v_mfma_f32_16x16x4_f32 v[228:231], v195, v215, v[228:231]
	v_mfma_f32_16x16x4_f32 v[232:235], v196, v215, v[232:235]
	v_mfma_f32_16x16x4_f32 v[236:239], v197, v215, v[236:239]
	ds_read_b128 v[198:201], v174 offset:1280
	ds_read_b128 v[202:205], v174 offset:1344
	ds_read_b128 v[206:209], v174 offset:1408
	ds_read_b128 v[210:213], v174 offset:1472
	ds_read_b32 v218, v171 offset:6144
	ds_read_b32 v219, v171 offset:6160
	ds_read_b32 v214, v169 offset:12288
	ds_read_b32 v215, v169 offset:13312
	v_mfma_f32_16x16x4_f32 v[224:227], v182, v88, v[224:227]
	v_mfma_f32_16x16x4_f32 v[228:231], v183, v88, v[228:231]
	v_mfma_f32_16x16x4_f32 v[232:235], v184, v88, v[232:235]
	v_mfma_f32_16x16x4_f32 v[236:239], v185, v88, v[236:239]
	v_mfma_f32_16x16x4_f32 v[224:227], v186, v89, v[224:227]
	v_mfma_f32_16x16x4_f32 v[228:231], v187, v89, v[228:231]
	v_mfma_f32_16x16x4_f32 v[232:235], v188, v89, v[232:235]
	v_mfma_f32_16x16x4_f32 v[236:239], v189, v89, v[236:239]
	v_add_u32_e32 v173, 0x880, v173
	v_add_u32_e32 v2, 0x880, v2
	v_add_u32_e32 v3, 0x880, v3
	v_add_u32_e32 v5, 0x880, v5
	ds_read2_b32 v[182:183], v173 offset0:0 offset1:16
	ds_read2_b32 v[184:185], v173 offset0:32 offset1:48
	ds_read2_b32 v[186:187], v2 offset0:0 offset1:16
	ds_read2_b32 v[188:189], v2 offset0:32 offset1:48
	ds_read2_b32 v[190:191], v3 offset0:0 offset1:16
	ds_read2_b32 v[192:193], v3 offset0:32 offset1:48
	ds_read2_b32 v[194:195], v5 offset0:0 offset1:16
	ds_read2_b32 v[196:197], v5 offset0:32 offset1:48
	ds_write2st64_b32 v175, v90, v91 offset0:40 offset1:44
	s_mov_b64 exec, s[14:15]
	ds_add_u32 v179, v241 offset:20
	s_mov_b64 exec, -1
	s_waitcnt lgkmcnt(14)
	v_pk_mul_f32 v[224:225], v[224:225], v[198:199]
	v_pk_mul_f32 v[226:227], v[226:227], v[200:201]
	v_pk_mul_f32 v[228:229], v[228:229], v[202:203]
	v_pk_mul_f32 v[230:231], v[230:231], v[204:205]
	v_mfma_f32_16x16x4_f32 v[36:39], v44, v224, 0
	v_mfma_f32_16x16x4_f32 v[40:43], v45, v225, 0
	v_mfma_f32_16x16x4_f32 v[36:39], v46, v226, v[36:39]
	v_mfma_f32_16x16x4_f32 v[40:43], v47, v227, v[40:43]
	v_pk_mul_f32 v[232:233], v[232:233], v[206:207]
	v_pk_mul_f32 v[234:235], v[234:235], v[208:209]
	v_mfma_f32_16x16x4_f32 v[36:39], v48, v228, v[36:39]
	v_mfma_f32_16x16x4_f32 v[40:43], v49, v229, v[40:43]
	v_mfma_f32_16x16x4_f32 v[36:39], v50, v230, v[36:39]
	v_mfma_f32_16x16x4_f32 v[40:43], v51, v231, v[40:43]
	v_pk_mul_f32 v[236:237], v[236:237], v[210:211]
	v_pk_mul_f32 v[238:239], v[238:239], v[212:213]
	v_mfma_f32_16x16x4_f32 v[36:39], v68, v232, v[36:39]
	v_mfma_f32_16x16x4_f32 v[40:43], v69, v233, v[40:43]
	v_mfma_f32_16x16x4_f32 v[36:39], v70, v234, v[36:39]
	v_mfma_f32_16x16x4_f32 v[40:43], v71, v235, v[40:43]
	v_mfma_f32_16x16x4_f32 v[36:39], v96, v236, v[36:39]
	v_mfma_f32_16x16x4_f32 v[40:43], v97, v237, v[40:43]
	v_mfma_f32_16x16x4_f32 v[36:39], v98, v238, v[36:39]
	v_mfma_f32_16x16x4_f32 v[40:43], v99, v239, v[40:43]
	s_waitcnt lgkmcnt(2)
	v_mfma_f32_16x16x4_f32 v[36:39], v216, v214, v[36:39]
	v_mfma_f32_16x16x4_f32 v[40:43], v217, v215, v[40:43]
	v_mfma_f32_16x16x4_f32 v[224:227], v190, v214, v[224:227]
	v_mfma_f32_16x16x4_f32 v[228:231], v191, v214, v[228:231]
	v_mfma_f32_16x16x4_f32 v[232:235], v192, v214, v[232:235]
	v_mfma_f32_16x16x4_f32 v[236:239], v193, v214, v[236:239]
	ds_read_b128 v[44:47], v168 offset:15232
	ds_read_b128 v[48:51], v168 offset:15296
	ds_read_b128 v[68:71], v168 offset:15360
	ds_read_b128 v[96:99], v168 offset:15424
	ds_read_b32 v216, v171 offset:7424
	ds_read_b32 v217, v171 offset:7440
	v_pk_add_f32 v[84:85], v[36:37], v[40:41]
	v_pk_add_f32 v[82:83], v[38:39], v[42:43]
	s_nop 1
	v_mfma_f32_16x16x4_f32 v[88:91], v218, v84, v[80:83]
	v_mfma_f32_16x16x4_f32 v[88:91], v219, v85, v[88:91]
	v_mfma_f32_16x16x4_f32 v[224:227], v194, v215, v[224:227]
	v_mfma_f32_16x16x4_f32 v[228:231], v195, v215, v[228:231]
	v_mfma_f32_16x16x4_f32 v[232:235], v196, v215, v[232:235]
	v_mfma_f32_16x16x4_f32 v[236:239], v197, v215, v[236:239]
	ds_read_b128 v[198:201], v174 offset:1536
	ds_read_b128 v[202:205], v174 offset:1600
	ds_read_b128 v[206:209], v174 offset:1664
	ds_read_b128 v[210:213], v174 offset:1728
	ds_read_b32 v218, v171 offset:7168
	ds_read_b32 v219, v171 offset:7184
	ds_read_b32 v214, v169 offset:14336
	ds_read_b32 v215, v169 offset:15360
	v_mfma_f32_16x16x4_f32 v[224:227], v182, v88, v[224:227]
	v_mfma_f32_16x16x4_f32 v[228:231], v183, v88, v[228:231]
	v_mfma_f32_16x16x4_f32 v[232:235], v184, v88, v[232:235]
	v_mfma_f32_16x16x4_f32 v[236:239], v185, v88, v[236:239]
	v_mfma_f32_16x16x4_f32 v[224:227], v186, v89, v[224:227]
	v_mfma_f32_16x16x4_f32 v[228:231], v187, v89, v[228:231]
	v_mfma_f32_16x16x4_f32 v[232:235], v188, v89, v[232:235]
	v_mfma_f32_16x16x4_f32 v[236:239], v189, v89, v[236:239]
	v_add_u32_e32 v173, 0x880, v173
	v_add_u32_e32 v2, 0x880, v2
	v_add_u32_e32 v3, 0x880, v3
	v_add_u32_e32 v5, 0x880, v5
	ds_read2_b32 v[182:183], v173 offset0:0 offset1:16
	ds_read2_b32 v[184:185], v173 offset0:32 offset1:48
	ds_read2_b32 v[186:187], v2 offset0:0 offset1:16
	ds_read2_b32 v[188:189], v2 offset0:32 offset1:48
	ds_read2_b32 v[190:191], v3 offset0:0 offset1:16
	ds_read2_b32 v[192:193], v3 offset0:32 offset1:48
	ds_read2_b32 v[194:195], v5 offset0:0 offset1:16
	ds_read2_b32 v[196:197], v5 offset0:32 offset1:48
	ds_write2st64_b32 v175, v90, v91 offset0:48 offset1:52
	s_mov_b64 exec, s[14:15]
	ds_add_u32 v179, v241 offset:24
	s_mov_b64 exec, -1
	s_waitcnt lgkmcnt(14)
	v_pk_mul_f32 v[224:225], v[224:225], v[198:199]
	v_pk_mul_f32 v[226:227], v[226:227], v[200:201]
	v_pk_mul_f32 v[228:229], v[228:229], v[202:203]
	v_pk_mul_f32 v[230:231], v[230:231], v[204:205]
	v_mfma_f32_16x16x4_f32 v[36:39], v44, v224, 0
	v_mfma_f32_16x16x4_f32 v[40:43], v45, v225, 0
	v_mfma_f32_16x16x4_f32 v[36:39], v46, v226, v[36:39]
	v_mfma_f32_16x16x4_f32 v[40:43], v47, v227, v[40:43]
	v_pk_mul_f32 v[232:233], v[232:233], v[206:207]
	v_pk_mul_f32 v[234:235], v[234:235], v[208:209]
	v_mfma_f32_16x16x4_f32 v[36:39], v48, v228, v[36:39]
	v_mfma_f32_16x16x4_f32 v[40:43], v49, v229, v[40:43]
	v_mfma_f32_16x16x4_f32 v[36:39], v50, v230, v[36:39]
	v_mfma_f32_16x16x4_f32 v[40:43], v51, v231, v[40:43]
	v_pk_mul_f32 v[236:237], v[236:237], v[210:211]
	v_pk_mul_f32 v[238:239], v[238:239], v[212:213]
	v_mfma_f32_16x16x4_f32 v[36:39], v68, v232, v[36:39]
	v_mfma_f32_16x16x4_f32 v[40:43], v69, v233, v[40:43]
	v_mfma_f32_16x16x4_f32 v[36:39], v70, v234, v[36:39]
	v_mfma_f32_16x16x4_f32 v[40:43], v71, v235, v[40:43]
	v_mfma_f32_16x16x4_f32 v[36:39], v96, v236, v[36:39]
	v_mfma_f32_16x16x4_f32 v[40:43], v97, v237, v[40:43]
	v_mfma_f32_16x16x4_f32 v[36:39], v98, v238, v[36:39]
	v_mfma_f32_16x16x4_f32 v[40:43], v99, v239, v[40:43]
	s_waitcnt lgkmcnt(2)
	v_mfma_f32_16x16x4_f32 v[36:39], v216, v214, v[36:39]
	v_mfma_f32_16x16x4_f32 v[40:43], v217, v215, v[40:43]
	v_mfma_f32_16x16x4_f32 v[224:227], v190, v214, v[224:227]
	v_mfma_f32_16x16x4_f32 v[228:231], v191, v214, v[228:231]
	v_mfma_f32_16x16x4_f32 v[232:235], v192, v214, v[232:235]
	v_mfma_f32_16x16x4_f32 v[236:239], v193, v214, v[236:239]
	ds_read_b128 v[44:47], v168 offset:17408
	ds_read_b128 v[48:51], v168 offset:17472
	ds_read_b128 v[68:71], v168 offset:17536
	ds_read_b128 v[96:99], v168 offset:17600
	ds_read_b32 v216, v171 offset:8448
	ds_read_b32 v217, v171 offset:8464
	v_pk_add_f32 v[84:85], v[36:37], v[40:41]
	v_pk_add_f32 v[82:83], v[38:39], v[42:43]
	s_nop 1
	v_mfma_f32_16x16x4_f32 v[88:91], v218, v84, v[80:83]
	v_mfma_f32_16x16x4_f32 v[88:91], v219, v85, v[88:91]
	v_mfma_f32_16x16x4_f32 v[224:227], v194, v215, v[224:227]
	v_mfma_f32_16x16x4_f32 v[228:231], v195, v215, v[228:231]
	v_mfma_f32_16x16x4_f32 v[232:235], v196, v215, v[232:235]
	v_mfma_f32_16x16x4_f32 v[236:239], v197, v215, v[236:239]
	ds_read_b128 v[198:201], v174 offset:1792
	ds_read_b128 v[202:205], v174 offset:1856
	ds_read_b128 v[206:209], v174 offset:1920
	ds_read_b128 v[210:213], v174 offset:1984
	ds_read_b32 v218, v171 offset:8192
	ds_read_b32 v219, v171 offset:8208
	ds_read_b32 v214, v169 offset:16384
	ds_read_b32 v215, v169 offset:17408
	v_mfma_f32_16x16x4_f32 v[224:227], v182, v88, v[224:227]
	v_mfma_f32_16x16x4_f32 v[228:231], v183, v88, v[228:231]
	v_mfma_f32_16x16x4_f32 v[232:235], v184, v88, v[232:235]
	v_mfma_f32_16x16x4_f32 v[236:239], v185, v88, v[236:239]
	v_mfma_f32_16x16x4_f32 v[224:227], v186, v89, v[224:227]
	v_mfma_f32_16x16x4_f32 v[228:231], v187, v89, v[228:231]
	v_mfma_f32_16x16x4_f32 v[232:235], v188, v89, v[232:235]
	v_mfma_f32_16x16x4_f32 v[236:239], v189, v89, v[236:239]
	v_add_u32_e32 v173, 0x880, v173
	v_add_u32_e32 v2, 0x880, v2
	v_add_u32_e32 v3, 0x880, v3
	v_add_u32_e32 v5, 0x880, v5
	ds_read2_b32 v[182:183], v173 offset0:0 offset1:16
	ds_read2_b32 v[184:185], v173 offset0:32 offset1:48
	ds_read2_b32 v[186:187], v2 offset0:0 offset1:16
	ds_read2_b32 v[188:189], v2 offset0:32 offset1:48
	ds_read2_b32 v[190:191], v3 offset0:0 offset1:16
	ds_read2_b32 v[192:193], v3 offset0:32 offset1:48
	ds_read2_b32 v[194:195], v5 offset0:0 offset1:16
	ds_read2_b32 v[196:197], v5 offset0:32 offset1:48
	ds_write2st64_b32 v175, v90, v91 offset0:56 offset1:60
	s_mov_b64 exec, s[14:15]
	ds_add_u32 v179, v241 offset:28
	s_mov_b64 exec, -1
	s_waitcnt lgkmcnt(0)
	s_nop 7
	v_pk_mul_f32 v[224:225], v[224:225], v[198:199]
	v_pk_mul_f32 v[226:227], v[226:227], v[200:201]
	v_pk_mul_f32 v[228:229], v[228:229], v[202:203]
	v_pk_mul_f32 v[230:231], v[230:231], v[204:205]
	v_pk_mul_f32 v[232:233], v[232:233], v[206:207]
	v_pk_mul_f32 v[234:235], v[234:235], v[208:209]
	v_pk_mul_f32 v[236:237], v[236:237], v[210:211]
	v_pk_mul_f32 v[238:239], v[238:239], v[212:213]
	s_branch .Lrw_done
